# P0 x-conversion loop fully unrolled (16 rows/wave) with depth-2 row prefetch: 16 loads in flight per wave, counted in-order vmcnt
# baseline (speedup 1.0000x reference)
; __device__ __forceinline__ unsigned cvt_pk_bf16(float lo, float hi) { unsigned r; asm("v_cvt_pk_bf16_f32 %0, %1, %2" : "=v"(r) : "v"(lo), "v"(hi)); return r; }
; __device__ __forceinline__ float wave_sum(float s, int) { s += dppf<0x128>(s); s += dppf<0x124>(s); s += dppf<0x122>(s); s += dppf<0x121>(s); return psum32(psum16(s)); }
; __device__ __forceinline__ void p0_prep(const Params& p, unsigned char* lds, int bid, int nb) {
;     ...
;     for (int row = bid * 8 + wid; row < T; row += nb * 8) {
;       const f32x4* src = (const f32x4*)(p.x + (size_t)row * D); float s = 0.f;
; #pragma unroll
;       for (int j = 0; j < 8; ++j) { const f32x4 v = src[lane + 64 * j]; s += v[0] * v[0] + v[1] * v[1] + v[2] * v[2] + v[3] * v[3];
;         u32x2 o; o[0] = cvt_pk_bf16(v[0], v[1]); o[1] = cvt_pk_bf16(v[2], v[3]); *(u32x2*)(xb + (size_t)row * D + (lane + 64 * j) * 4) = o;
;         unsigned q8 = __builtin_amdgcn_cvt_pk_fp8_f32(v[0], v[1], 0, false); q8 = __builtin_amdgcn_cvt_pk_fp8_f32(v[2], v[3], q8, true); *(unsigned*)(xq + (size_t)row * D + (lane + 64 * j) * 4) = q8; }
;       s = wave_sum(s, lane); if (lane == 0) ss0[row] = s;
;     }
.LBB0_2:
	s_or_b64 exec, exec, s[4:5]
	s_lshl_b32 s4, s88, 3
	v_mov_b32_e32 v22, v200
	s_mov_b32 s2, s4
	v_writelane_b32 v254, s2, 22
	v_ashrrev_i32_e32 v2, 6, v22
	v_add_u32_e32 v12, s4, v2
	v_writelane_b32 v254, s3, 23
	s_mov_b32 s2, 0x8000
	v_and_b32_e32 v1, 63, v22
	v_cmp_gt_i32_e32 vcc, s2, v12
	s_and_saveexec_b64 s[6:7], vcc
	s_cbranch_execz .LBB0_7
	s_load_dwordx4 s[12:15], s[0:1], 0x80
	v_readlane_b32 s2, v254, 22
	v_ashrrev_i32_e32 v3, 31, v2
	s_mov_b32 s4, s2
	s_ashr_i32 s5, s2, 31
	v_readlane_b32 s3, v254, 23
	v_lshl_add_u64 v[10:11], v[2:3], 0, s[4:5]
	s_load_dwordx16 s[36:51], s[0:1], 0x0
	v_writelane_b32 v254, s2, 22
	v_lshlrev_b64 v[6:7], 11, v[10:11]
	s_waitcnt lgkmcnt(0)
	v_lshl_add_u64 v[4:5], v[10:11], 2, s[14:15]
	v_writelane_b32 v254, s3, 23
	s_mov_b64 s[2:3], 0x3eb00000
	v_lshl_or_b32 v6, v1, 2, v6
	v_lshlrev_b64 v[8:9], 12, v[10:11]
	v_lshl_add_u64 v[4:5], v[4:5], 0, s[2:3]
	v_lshl_add_u64 v[6:7], s[14:15], 0, v[6:7]
	s_mov_b64 s[2:3], 0x28000400
	v_lshl_or_b32 v8, v1, 3, v8
	v_lshlrev_b64 v[10:11], 13, v[10:11]
	s_lshl_b32 s8, s89, 3
	v_lshl_add_u64 v[6:7], v[6:7], 0, s[2:3]
	v_lshl_add_u64 v[8:9], s[14:15], 0, v[8:9]
	s_mov_b64 s[2:3], 0x20000800
	v_lshl_or_b32 v10, v1, 4, v10
	s_ashr_i32 s9, s8, 31
	v_lshl_add_u64 v[8:9], v[8:9], 0, s[2:3]
	v_lshl_add_u64 v[10:11], s[36:37], 0, v[10:11]
	s_mov_b64 s[2:3], 0x1000
	v_cmp_eq_u32_e32 vcc, 0, v1
	s_lshl_b64 s[10:11], s[8:9], 2
	s_lshl_b64 s[12:13], s[8:9], 11
	s_lshl_b64 s[14:15], s[8:9], 12
	v_lshl_add_u64 v[10:11], v[10:11], 0, s[2:3]
	s_lshl_b64 s[16:17], s[8:9], 13
	s_mov_b64 s[18:19], 0
	s_movk_i32 s2, 0x7fff
	s_cmp_lg_u32 s89, 0x100
	s_cbranch_scc1 .Lx_generic
	global_load_dwordx4 v[14:17], v[10:11], off offset:-4096
	global_load_dwordx4 v[18:21], v[10:11], off offset:-3072
	global_load_dwordx4 v[24:27], v[10:11], off offset:-2048
	global_load_dwordx4 v[28:31], v[10:11], off offset:-1024
	global_load_dwordx4 v[32:35], v[10:11], off
	global_load_dwordx4 v[36:39], v[10:11], off offset:1024
	global_load_dwordx4 v[40:43], v[10:11], off offset:2048
	global_load_dwordx4 v[44:47], v[10:11], off offset:3072
	v_lshl_add_u64 v[82:83], v[10:11], 0, s[16:17]
	global_load_dwordx4 v[84:87], v[82:83], off offset:-4096
	global_load_dwordx4 v[88:91], v[82:83], off offset:-3072
	global_load_dwordx4 v[92:95], v[82:83], off offset:-2048
	global_load_dwordx4 v[96:99], v[82:83], off offset:-1024
	global_load_dwordx4 v[100:103], v[82:83], off
	global_load_dwordx4 v[104:107], v[82:83], off offset:1024
	global_load_dwordx4 v[108:111], v[82:83], off offset:2048
	global_load_dwordx4 v[112:115], v[82:83], off offset:3072
	v_lshl_add_u64 v[82:83], v[82:83], 0, s[16:17]
	s_waitcnt vmcnt(15)
	v_cvt_pk_bf16_f32 v56, v14, v15
	v_cvt_pk_bf16_f32 v57, v16, v17
	v_cvt_pk_fp8_f32 v72, v14, v15
	v_mul_f32_e32 v13, v15, v15
	v_fmac_f32_e32 v13, v14, v14
	v_fmac_f32_e32 v13, v16, v16
	v_cvt_pk_fp8_f32 v72, v16, v17 op_sel:[0,0,1]
	v_fmac_f32_e32 v13, v17, v17
	s_waitcnt vmcnt(14)
	v_cvt_pk_bf16_f32 v58, v18, v19
	v_cvt_pk_bf16_f32 v59, v20, v21
	v_cvt_pk_fp8_f32 v73, v18, v19
	v_mul_f32_e32 v80, v19, v19
	v_fmac_f32_e32 v80, v18, v18
	v_fmac_f32_e32 v80, v20, v20
	v_cvt_pk_fp8_f32 v73, v20, v21 op_sel:[0,0,1]
	v_fmac_f32_e32 v80, v21, v21
	v_add_f32_e32 v13, v13, v80
	s_waitcnt vmcnt(13)
	v_cvt_pk_bf16_f32 v60, v24, v25
	v_cvt_pk_bf16_f32 v61, v26, v27
	v_cvt_pk_fp8_f32 v74, v24, v25
	v_mul_f32_e32 v80, v25, v25
	v_fmac_f32_e32 v80, v24, v24
	v_fmac_f32_e32 v80, v26, v26
	v_cvt_pk_fp8_f32 v74, v26, v27 op_sel:[0,0,1]
	v_fmac_f32_e32 v80, v27, v27
	v_add_f32_e32 v13, v13, v80
	s_waitcnt vmcnt(12)
	v_cvt_pk_bf16_f32 v62, v28, v29
	v_cvt_pk_bf16_f32 v63, v30, v31
	v_cvt_pk_fp8_f32 v75, v28, v29
	v_mul_f32_e32 v80, v29, v29
	v_fmac_f32_e32 v80, v28, v28
	v_fmac_f32_e32 v80, v30, v30
	v_cvt_pk_fp8_f32 v75, v30, v31 op_sel:[0,0,1]
	v_fmac_f32_e32 v80, v31, v31
	v_add_f32_e32 v13, v13, v80
	s_waitcnt vmcnt(11)
	v_cvt_pk_bf16_f32 v64, v32, v33
	v_cvt_pk_bf16_f32 v65, v34, v35
	v_cvt_pk_fp8_f32 v76, v32, v33
	v_mul_f32_e32 v80, v33, v33
	v_fmac_f32_e32 v80, v32, v32
	v_fmac_f32_e32 v80, v34, v34
	v_cvt_pk_fp8_f32 v76, v34, v35 op_sel:[0,0,1]
	v_fmac_f32_e32 v80, v35, v35
	v_add_f32_e32 v13, v13, v80
	s_waitcnt vmcnt(10)
	v_cvt_pk_bf16_f32 v66, v36, v37
	v_cvt_pk_bf16_f32 v67, v38, v39
	v_cvt_pk_fp8_f32 v77, v36, v37
	v_mul_f32_e32 v80, v37, v37
	v_fmac_f32_e32 v80, v36, v36
	v_fmac_f32_e32 v80, v38, v38
	v_cvt_pk_fp8_f32 v77, v38, v39 op_sel:[0,0,1]
	v_fmac_f32_e32 v80, v39, v39
	v_add_f32_e32 v13, v13, v80
	s_waitcnt vmcnt(9)
	v_cvt_pk_bf16_f32 v68, v40, v41
	v_cvt_pk_bf16_f32 v69, v42, v43
	v_cvt_pk_fp8_f32 v78, v40, v41
	v_mul_f32_e32 v80, v41, v41
	v_fmac_f32_e32 v80, v40, v40
	v_fmac_f32_e32 v80, v42, v42
	v_cvt_pk_fp8_f32 v78, v42, v43 op_sel:[0,0,1]
	v_fmac_f32_e32 v80, v43, v43
	v_add_f32_e32 v13, v13, v80
	s_waitcnt vmcnt(8)
; __device__ __forceinline__ unsigned cvt_pk_bf16(float lo, float hi) { unsigned r; asm("v_cvt_pk_bf16_f32 %0, %1, %2" : "=v"(r) : "v"(lo), "v"(hi)); return r; }
; __device__ __forceinline__ float wave_sum(float s, int) { s += dppf<0x128>(s); s += dppf<0x124>(s); s += dppf<0x122>(s); s += dppf<0x121>(s); return psum32(psum16(s)); }
; __device__ __forceinline__ void p0_prep(const Params& p, unsigned char* lds, int bid, int nb) {
;     ...
;     for (int row = bid * 8 + wid; row < T; row += nb * 8) {
;       const f32x4* src = (const f32x4*)(p.x + (size_t)row * D); float s = 0.f;
; #pragma unroll
;       for (int j = 0; j < 8; ++j) { const f32x4 v = src[lane + 64 * j]; s += v[0] * v[0] + v[1] * v[1] + v[2] * v[2] + v[3] * v[3];
;         u32x2 o; o[0] = cvt_pk_bf16(v[0], v[1]); o[1] = cvt_pk_bf16(v[2], v[3]); *(u32x2*)(xb + (size_t)row * D + (lane + 64 * j) * 4) = o;
;         unsigned q8 = __builtin_amdgcn_cvt_pk_fp8_f32(v[0], v[1], 0, false); q8 = __builtin_amdgcn_cvt_pk_fp8_f32(v[2], v[3], q8, true); *(unsigned*)(xq + (size_t)row * D + (lane + 64 * j) * 4) = q8; }
;       s = wave_sum(s, lane); if (lane == 0) ss0[row] = s;
;     }
	v_cvt_pk_bf16_f32 v70, v44, v45
	v_cvt_pk_bf16_f32 v71, v46, v47
	v_cvt_pk_fp8_f32 v79, v44, v45
	v_mul_f32_e32 v80, v45, v45
	v_fmac_f32_e32 v80, v44, v44
	v_fmac_f32_e32 v80, v46, v46
	v_cvt_pk_fp8_f32 v79, v46, v47 op_sel:[0,0,1]
	v_fmac_f32_e32 v80, v47, v47
	v_add_f32_e32 v13, v13, v80
	global_load_dwordx4 v[14:17], v[82:83], off offset:-4096
	global_load_dwordx4 v[18:21], v[82:83], off offset:-3072
	global_load_dwordx4 v[24:27], v[82:83], off offset:-2048
	global_load_dwordx4 v[28:31], v[82:83], off offset:-1024
	global_load_dwordx4 v[32:35], v[82:83], off
	global_load_dwordx4 v[36:39], v[82:83], off offset:1024
	global_load_dwordx4 v[40:43], v[82:83], off offset:2048
	global_load_dwordx4 v[44:47], v[82:83], off offset:3072
	v_lshl_add_u64 v[82:83], v[82:83], 0, s[16:17]
	global_store_dwordx2 v[8:9], v[56:57], off offset:-2048
	global_store_dword v[6:7], v72, off offset:-1024
	global_store_dwordx2 v[8:9], v[58:59], off offset:-1536
	global_store_dword v[6:7], v73, off offset:-768
	global_store_dwordx2 v[8:9], v[60:61], off offset:-1024
	global_store_dword v[6:7], v74, off offset:-512
	global_store_dwordx2 v[8:9], v[62:63], off offset:-512
	global_store_dword v[6:7], v75, off offset:-256
	global_store_dwordx2 v[8:9], v[64:65], off
	global_store_dword v[6:7], v76, off
	global_store_dwordx2 v[8:9], v[66:67], off offset:512
	global_store_dword v[6:7], v77, off offset:256
	global_store_dwordx2 v[8:9], v[68:69], off offset:1024
	global_store_dword v[6:7], v78, off offset:512
	global_store_dwordx2 v[8:9], v[70:71], off offset:1536
	global_store_dword v[6:7], v79, off offset:768
	v_add_f32_dpp v13, v13, v13 row_ror:8 row_mask:0xf bank_mask:0xf bound_ctrl:1
	s_nop 1
	v_add_f32_dpp v13, v13, v13 row_ror:4 row_mask:0xf bank_mask:0xf bound_ctrl:1
	s_nop 1
	v_add_f32_dpp v13, v13, v13 row_ror:2 row_mask:0xf bank_mask:0xf bound_ctrl:1
	s_nop 1
	v_add_f32_dpp v3, v13, v13 row_ror:1 row_mask:0xf bank_mask:0xf bound_ctrl:1
	v_mov_b32_e32 v13, v3
	s_nop 1
	v_permlane16_swap_b32_e32 v3, v13
	v_add_f32_e32 v3, v3, v13
	v_mov_b32_e32 v13, v3
	s_nop 1
	v_permlane32_swap_b32_e32 v3, v13
	s_and_saveexec_b64 s[4:5], vcc
	v_add_f32_e32 v3, v3, v13
	global_store_dword v[4:5], v3, off
	s_or_b64 exec, exec, s[4:5]
	v_lshl_add_u64 v[4:5], v[4:5], 0, s[10:11]
	v_lshl_add_u64 v[6:7], v[6:7], 0, s[12:13]
	v_lshl_add_u64 v[8:9], v[8:9], 0, s[14:15]
	s_waitcnt vmcnt(32)
	v_cvt_pk_bf16_f32 v56, v84, v85
	v_cvt_pk_bf16_f32 v57, v86, v87
	v_cvt_pk_fp8_f32 v72, v84, v85
	v_mul_f32_e32 v13, v85, v85
	v_fmac_f32_e32 v13, v84, v84
	v_fmac_f32_e32 v13, v86, v86
	v_cvt_pk_fp8_f32 v72, v86, v87 op_sel:[0,0,1]
	v_fmac_f32_e32 v13, v87, v87
	s_waitcnt vmcnt(31)
	v_cvt_pk_bf16_f32 v58, v88, v89
	v_cvt_pk_bf16_f32 v59, v90, v91
	v_cvt_pk_fp8_f32 v73, v88, v89
	v_mul_f32_e32 v80, v89, v89
	v_fmac_f32_e32 v80, v88, v88
	v_fmac_f32_e32 v80, v90, v90
	v_cvt_pk_fp8_f32 v73, v90, v91 op_sel:[0,0,1]
	v_fmac_f32_e32 v80, v91, v91
	v_add_f32_e32 v13, v13, v80
	s_waitcnt vmcnt(30)
	v_cvt_pk_bf16_f32 v60, v92, v93
	v_cvt_pk_bf16_f32 v61, v94, v95
	v_cvt_pk_fp8_f32 v74, v92, v93
	v_mul_f32_e32 v80, v93, v93
	v_fmac_f32_e32 v80, v92, v92
	v_fmac_f32_e32 v80, v94, v94
	v_cvt_pk_fp8_f32 v74, v94, v95 op_sel:[0,0,1]
	v_fmac_f32_e32 v80, v95, v95
	v_add_f32_e32 v13, v13, v80
	s_waitcnt vmcnt(29)
	v_cvt_pk_bf16_f32 v62, v96, v97
	v_cvt_pk_bf16_f32 v63, v98, v99
	v_cvt_pk_fp8_f32 v75, v96, v97
	v_mul_f32_e32 v80, v97, v97
	v_fmac_f32_e32 v80, v96, v96
	v_fmac_f32_e32 v80, v98, v98
	v_cvt_pk_fp8_f32 v75, v98, v99 op_sel:[0,0,1]
	v_fmac_f32_e32 v80, v99, v99
	v_add_f32_e32 v13, v13, v80
	s_waitcnt vmcnt(28)
	v_cvt_pk_bf16_f32 v64, v100, v101
	v_cvt_pk_bf16_f32 v65, v102, v103
	v_cvt_pk_fp8_f32 v76, v100, v101
	v_mul_f32_e32 v80, v101, v101
	v_fmac_f32_e32 v80, v100, v100
	v_fmac_f32_e32 v80, v102, v102
	v_cvt_pk_fp8_f32 v76, v102, v103 op_sel:[0,0,1]
	v_fmac_f32_e32 v80, v103, v103
	v_add_f32_e32 v13, v13, v80
	s_waitcnt vmcnt(27)
	v_cvt_pk_bf16_f32 v66, v104, v105
	v_cvt_pk_bf16_f32 v67, v106, v107
	v_cvt_pk_fp8_f32 v77, v104, v105
	v_mul_f32_e32 v80, v105, v105
	v_fmac_f32_e32 v80, v104, v104
	v_fmac_f32_e32 v80, v106, v106
	v_cvt_pk_fp8_f32 v77, v106, v107 op_sel:[0,0,1]
	v_fmac_f32_e32 v80, v107, v107
	v_add_f32_e32 v13, v13, v80
	s_waitcnt vmcnt(26)
	v_cvt_pk_bf16_f32 v68, v108, v109
	v_cvt_pk_bf16_f32 v69, v110, v111
	v_cvt_pk_fp8_f32 v78, v108, v109
	v_mul_f32_e32 v80, v109, v109
	v_fmac_f32_e32 v80, v108, v108
	v_fmac_f32_e32 v80, v110, v110
	v_cvt_pk_fp8_f32 v78, v110, v111 op_sel:[0,0,1]
	v_fmac_f32_e32 v80, v111, v111
	v_add_f32_e32 v13, v13, v80
	s_waitcnt vmcnt(25)
; __device__ __forceinline__ unsigned cvt_pk_bf16(float lo, float hi) { unsigned r; asm("v_cvt_pk_bf16_f32 %0, %1, %2" : "=v"(r) : "v"(lo), "v"(hi)); return r; }
; __device__ __forceinline__ float wave_sum(float s, int) { s += dppf<0x128>(s); s += dppf<0x124>(s); s += dppf<0x122>(s); s += dppf<0x121>(s); return psum32(psum16(s)); }
; __device__ __forceinline__ void p0_prep(const Params& p, unsigned char* lds, int bid, int nb) {
;     ...
;     for (int row = bid * 8 + wid; row < T; row += nb * 8) {
;       const f32x4* src = (const f32x4*)(p.x + (size_t)row * D); float s = 0.f;
; #pragma unroll
;       for (int j = 0; j < 8; ++j) { const f32x4 v = src[lane + 64 * j]; s += v[0] * v[0] + v[1] * v[1] + v[2] * v[2] + v[3] * v[3];
;         u32x2 o; o[0] = cvt_pk_bf16(v[0], v[1]); o[1] = cvt_pk_bf16(v[2], v[3]); *(u32x2*)(xb + (size_t)row * D + (lane + 64 * j) * 4) = o;
;         unsigned q8 = __builtin_amdgcn_cvt_pk_fp8_f32(v[0], v[1], 0, false); q8 = __builtin_amdgcn_cvt_pk_fp8_f32(v[2], v[3], q8, true); *(unsigned*)(xq + (size_t)row * D + (lane + 64 * j) * 4) = q8; }
;       s = wave_sum(s, lane); if (lane == 0) ss0[row] = s;
;     }
	v_cvt_pk_bf16_f32 v70, v112, v113
	v_cvt_pk_bf16_f32 v71, v114, v115
	v_cvt_pk_fp8_f32 v79, v112, v113
	v_mul_f32_e32 v80, v113, v113
	v_fmac_f32_e32 v80, v112, v112
	v_fmac_f32_e32 v80, v114, v114
	v_cvt_pk_fp8_f32 v79, v114, v115 op_sel:[0,0,1]
	v_fmac_f32_e32 v80, v115, v115
	v_add_f32_e32 v13, v13, v80
	global_load_dwordx4 v[84:87], v[82:83], off offset:-4096
	global_load_dwordx4 v[88:91], v[82:83], off offset:-3072
	global_load_dwordx4 v[92:95], v[82:83], off offset:-2048
	global_load_dwordx4 v[96:99], v[82:83], off offset:-1024
	global_load_dwordx4 v[100:103], v[82:83], off
	global_load_dwordx4 v[104:107], v[82:83], off offset:1024
	global_load_dwordx4 v[108:111], v[82:83], off offset:2048
	global_load_dwordx4 v[112:115], v[82:83], off offset:3072
	v_lshl_add_u64 v[82:83], v[82:83], 0, s[16:17]
	global_store_dwordx2 v[8:9], v[56:57], off offset:-2048
	global_store_dword v[6:7], v72, off offset:-1024
	global_store_dwordx2 v[8:9], v[58:59], off offset:-1536
	global_store_dword v[6:7], v73, off offset:-768
	global_store_dwordx2 v[8:9], v[60:61], off offset:-1024
	global_store_dword v[6:7], v74, off offset:-512
	global_store_dwordx2 v[8:9], v[62:63], off offset:-512
	global_store_dword v[6:7], v75, off offset:-256
	global_store_dwordx2 v[8:9], v[64:65], off
	global_store_dword v[6:7], v76, off
	global_store_dwordx2 v[8:9], v[66:67], off offset:512
	global_store_dword v[6:7], v77, off offset:256
	global_store_dwordx2 v[8:9], v[68:69], off offset:1024
	global_store_dword v[6:7], v78, off offset:512
	global_store_dwordx2 v[8:9], v[70:71], off offset:1536
	global_store_dword v[6:7], v79, off offset:768
	v_add_f32_dpp v13, v13, v13 row_ror:8 row_mask:0xf bank_mask:0xf bound_ctrl:1
	s_nop 1
	v_add_f32_dpp v13, v13, v13 row_ror:4 row_mask:0xf bank_mask:0xf bound_ctrl:1
	s_nop 1
	v_add_f32_dpp v13, v13, v13 row_ror:2 row_mask:0xf bank_mask:0xf bound_ctrl:1
	s_nop 1
	v_add_f32_dpp v3, v13, v13 row_ror:1 row_mask:0xf bank_mask:0xf bound_ctrl:1
	v_mov_b32_e32 v13, v3
	s_nop 1
	v_permlane16_swap_b32_e32 v3, v13
	v_add_f32_e32 v3, v3, v13
	v_mov_b32_e32 v13, v3
	s_nop 1
	v_permlane32_swap_b32_e32 v3, v13
	s_and_saveexec_b64 s[4:5], vcc
	v_add_f32_e32 v3, v3, v13
	global_store_dword v[4:5], v3, off
	s_or_b64 exec, exec, s[4:5]
	v_lshl_add_u64 v[4:5], v[4:5], 0, s[10:11]
	v_lshl_add_u64 v[6:7], v[6:7], 0, s[12:13]
	v_lshl_add_u64 v[8:9], v[8:9], 0, s[14:15]
	s_waitcnt vmcnt(49)
	v_cvt_pk_bf16_f32 v56, v14, v15
	v_cvt_pk_bf16_f32 v57, v16, v17
	v_cvt_pk_fp8_f32 v72, v14, v15
	v_mul_f32_e32 v13, v15, v15
	v_fmac_f32_e32 v13, v14, v14
	v_fmac_f32_e32 v13, v16, v16
	v_cvt_pk_fp8_f32 v72, v16, v17 op_sel:[0,0,1]
	v_fmac_f32_e32 v13, v17, v17
	s_waitcnt vmcnt(48)
	v_cvt_pk_bf16_f32 v58, v18, v19
	v_cvt_pk_bf16_f32 v59, v20, v21
	v_cvt_pk_fp8_f32 v73, v18, v19
	v_mul_f32_e32 v80, v19, v19
	v_fmac_f32_e32 v80, v18, v18
	v_fmac_f32_e32 v80, v20, v20
	v_cvt_pk_fp8_f32 v73, v20, v21 op_sel:[0,0,1]
	v_fmac_f32_e32 v80, v21, v21
	v_add_f32_e32 v13, v13, v80
	s_waitcnt vmcnt(47)
	v_cvt_pk_bf16_f32 v60, v24, v25
	v_cvt_pk_bf16_f32 v61, v26, v27
	v_cvt_pk_fp8_f32 v74, v24, v25
	v_mul_f32_e32 v80, v25, v25
	v_fmac_f32_e32 v80, v24, v24
	v_fmac_f32_e32 v80, v26, v26
	v_cvt_pk_fp8_f32 v74, v26, v27 op_sel:[0,0,1]
	v_fmac_f32_e32 v80, v27, v27
	v_add_f32_e32 v13, v13, v80
	s_waitcnt vmcnt(46)
	v_cvt_pk_bf16_f32 v62, v28, v29
	v_cvt_pk_bf16_f32 v63, v30, v31
	v_cvt_pk_fp8_f32 v75, v28, v29
	v_mul_f32_e32 v80, v29, v29
	v_fmac_f32_e32 v80, v28, v28
	v_fmac_f32_e32 v80, v30, v30
	v_cvt_pk_fp8_f32 v75, v30, v31 op_sel:[0,0,1]
	v_fmac_f32_e32 v80, v31, v31
	v_add_f32_e32 v13, v13, v80
	s_waitcnt vmcnt(45)
	v_cvt_pk_bf16_f32 v64, v32, v33
	v_cvt_pk_bf16_f32 v65, v34, v35
	v_cvt_pk_fp8_f32 v76, v32, v33
	v_mul_f32_e32 v80, v33, v33
	v_fmac_f32_e32 v80, v32, v32
	v_fmac_f32_e32 v80, v34, v34
	v_cvt_pk_fp8_f32 v76, v34, v35 op_sel:[0,0,1]
	v_fmac_f32_e32 v80, v35, v35
	v_add_f32_e32 v13, v13, v80
	s_waitcnt vmcnt(44)
	v_cvt_pk_bf16_f32 v66, v36, v37
	v_cvt_pk_bf16_f32 v67, v38, v39
	v_cvt_pk_fp8_f32 v77, v36, v37
	v_mul_f32_e32 v80, v37, v37
	v_fmac_f32_e32 v80, v36, v36
	v_fmac_f32_e32 v80, v38, v38
	v_cvt_pk_fp8_f32 v77, v38, v39 op_sel:[0,0,1]
	v_fmac_f32_e32 v80, v39, v39
	v_add_f32_e32 v13, v13, v80
	s_waitcnt vmcnt(43)
	v_cvt_pk_bf16_f32 v68, v40, v41
	v_cvt_pk_bf16_f32 v69, v42, v43
	v_cvt_pk_fp8_f32 v78, v40, v41
	v_mul_f32_e32 v80, v41, v41
	v_fmac_f32_e32 v80, v40, v40
	v_fmac_f32_e32 v80, v42, v42
	v_cvt_pk_fp8_f32 v78, v42, v43 op_sel:[0,0,1]
	v_fmac_f32_e32 v80, v43, v43
	v_add_f32_e32 v13, v13, v80
	s_waitcnt vmcnt(42)
; __device__ __forceinline__ unsigned cvt_pk_bf16(float lo, float hi) { unsigned r; asm("v_cvt_pk_bf16_f32 %0, %1, %2" : "=v"(r) : "v"(lo), "v"(hi)); return r; }
; __device__ __forceinline__ float wave_sum(float s, int) { s += dppf<0x128>(s); s += dppf<0x124>(s); s += dppf<0x122>(s); s += dppf<0x121>(s); return psum32(psum16(s)); }
; __device__ __forceinline__ void p0_prep(const Params& p, unsigned char* lds, int bid, int nb) {
;     ...
;     for (int row = bid * 8 + wid; row < T; row += nb * 8) {
;       const f32x4* src = (const f32x4*)(p.x + (size_t)row * D); float s = 0.f;
; #pragma unroll
;       for (int j = 0; j < 8; ++j) { const f32x4 v = src[lane + 64 * j]; s += v[0] * v[0] + v[1] * v[1] + v[2] * v[2] + v[3] * v[3];
;         u32x2 o; o[0] = cvt_pk_bf16(v[0], v[1]); o[1] = cvt_pk_bf16(v[2], v[3]); *(u32x2*)(xb + (size_t)row * D + (lane + 64 * j) * 4) = o;
;         unsigned q8 = __builtin_amdgcn_cvt_pk_fp8_f32(v[0], v[1], 0, false); q8 = __builtin_amdgcn_cvt_pk_fp8_f32(v[2], v[3], q8, true); *(unsigned*)(xq + (size_t)row * D + (lane + 64 * j) * 4) = q8; }
;       s = wave_sum(s, lane); if (lane == 0) ss0[row] = s;
;     }
	v_cvt_pk_bf16_f32 v70, v44, v45
	v_cvt_pk_bf16_f32 v71, v46, v47
	v_cvt_pk_fp8_f32 v79, v44, v45
	v_mul_f32_e32 v80, v45, v45
	v_fmac_f32_e32 v80, v44, v44
	v_fmac_f32_e32 v80, v46, v46
	v_cvt_pk_fp8_f32 v79, v46, v47 op_sel:[0,0,1]
	v_fmac_f32_e32 v80, v47, v47
	v_add_f32_e32 v13, v13, v80
	global_load_dwordx4 v[14:17], v[82:83], off offset:-4096
	global_load_dwordx4 v[18:21], v[82:83], off offset:-3072
	global_load_dwordx4 v[24:27], v[82:83], off offset:-2048
	global_load_dwordx4 v[28:31], v[82:83], off offset:-1024
	global_load_dwordx4 v[32:35], v[82:83], off
	global_load_dwordx4 v[36:39], v[82:83], off offset:1024
	global_load_dwordx4 v[40:43], v[82:83], off offset:2048
	global_load_dwordx4 v[44:47], v[82:83], off offset:3072
	v_lshl_add_u64 v[82:83], v[82:83], 0, s[16:17]
	global_store_dwordx2 v[8:9], v[56:57], off offset:-2048
	global_store_dword v[6:7], v72, off offset:-1024
	global_store_dwordx2 v[8:9], v[58:59], off offset:-1536
	global_store_dword v[6:7], v73, off offset:-768
	global_store_dwordx2 v[8:9], v[60:61], off offset:-1024
	global_store_dword v[6:7], v74, off offset:-512
	global_store_dwordx2 v[8:9], v[62:63], off offset:-512
	global_store_dword v[6:7], v75, off offset:-256
	global_store_dwordx2 v[8:9], v[64:65], off
	global_store_dword v[6:7], v76, off
	global_store_dwordx2 v[8:9], v[66:67], off offset:512
	global_store_dword v[6:7], v77, off offset:256
	global_store_dwordx2 v[8:9], v[68:69], off offset:1024
	global_store_dword v[6:7], v78, off offset:512
	global_store_dwordx2 v[8:9], v[70:71], off offset:1536
	global_store_dword v[6:7], v79, off offset:768
	v_add_f32_dpp v13, v13, v13 row_ror:8 row_mask:0xf bank_mask:0xf bound_ctrl:1
	s_nop 1
	v_add_f32_dpp v13, v13, v13 row_ror:4 row_mask:0xf bank_mask:0xf bound_ctrl:1
	s_nop 1
	v_add_f32_dpp v13, v13, v13 row_ror:2 row_mask:0xf bank_mask:0xf bound_ctrl:1
	s_nop 1
	v_add_f32_dpp v3, v13, v13 row_ror:1 row_mask:0xf bank_mask:0xf bound_ctrl:1
	v_mov_b32_e32 v13, v3
	s_nop 1
	v_permlane16_swap_b32_e32 v3, v13
	v_add_f32_e32 v3, v3, v13
	v_mov_b32_e32 v13, v3
	s_nop 1
	v_permlane32_swap_b32_e32 v3, v13
	s_and_saveexec_b64 s[4:5], vcc
	v_add_f32_e32 v3, v3, v13
	global_store_dword v[4:5], v3, off
	s_or_b64 exec, exec, s[4:5]
	v_lshl_add_u64 v[4:5], v[4:5], 0, s[10:11]
	v_lshl_add_u64 v[6:7], v[6:7], 0, s[12:13]
	v_lshl_add_u64 v[8:9], v[8:9], 0, s[14:15]
	s_waitcnt vmcnt(49)
	v_cvt_pk_bf16_f32 v56, v84, v85
	v_cvt_pk_bf16_f32 v57, v86, v87
	v_cvt_pk_fp8_f32 v72, v84, v85
	v_mul_f32_e32 v13, v85, v85
	v_fmac_f32_e32 v13, v84, v84
	v_fmac_f32_e32 v13, v86, v86
	v_cvt_pk_fp8_f32 v72, v86, v87 op_sel:[0,0,1]
	v_fmac_f32_e32 v13, v87, v87
	s_waitcnt vmcnt(48)
	v_cvt_pk_bf16_f32 v58, v88, v89
	v_cvt_pk_bf16_f32 v59, v90, v91
	v_cvt_pk_fp8_f32 v73, v88, v89
	v_mul_f32_e32 v80, v89, v89
	v_fmac_f32_e32 v80, v88, v88
	v_fmac_f32_e32 v80, v90, v90
	v_cvt_pk_fp8_f32 v73, v90, v91 op_sel:[0,0,1]
	v_fmac_f32_e32 v80, v91, v91
	v_add_f32_e32 v13, v13, v80
	s_waitcnt vmcnt(47)
	v_cvt_pk_bf16_f32 v60, v92, v93
	v_cvt_pk_bf16_f32 v61, v94, v95
	v_cvt_pk_fp8_f32 v74, v92, v93
	v_mul_f32_e32 v80, v93, v93
	v_fmac_f32_e32 v80, v92, v92
	v_fmac_f32_e32 v80, v94, v94
	v_cvt_pk_fp8_f32 v74, v94, v95 op_sel:[0,0,1]
	v_fmac_f32_e32 v80, v95, v95
	v_add_f32_e32 v13, v13, v80
	s_waitcnt vmcnt(46)
	v_cvt_pk_bf16_f32 v62, v96, v97
	v_cvt_pk_bf16_f32 v63, v98, v99
	v_cvt_pk_fp8_f32 v75, v96, v97
	v_mul_f32_e32 v80, v97, v97
	v_fmac_f32_e32 v80, v96, v96
	v_fmac_f32_e32 v80, v98, v98
	v_cvt_pk_fp8_f32 v75, v98, v99 op_sel:[0,0,1]
	v_fmac_f32_e32 v80, v99, v99
	v_add_f32_e32 v13, v13, v80
	s_waitcnt vmcnt(45)
	v_cvt_pk_bf16_f32 v64, v100, v101
	v_cvt_pk_bf16_f32 v65, v102, v103
	v_cvt_pk_fp8_f32 v76, v100, v101
	v_mul_f32_e32 v80, v101, v101
	v_fmac_f32_e32 v80, v100, v100
	v_fmac_f32_e32 v80, v102, v102
	v_cvt_pk_fp8_f32 v76, v102, v103 op_sel:[0,0,1]
	v_fmac_f32_e32 v80, v103, v103
	v_add_f32_e32 v13, v13, v80
	s_waitcnt vmcnt(44)
	v_cvt_pk_bf16_f32 v66, v104, v105
	v_cvt_pk_bf16_f32 v67, v106, v107
	v_cvt_pk_fp8_f32 v77, v104, v105
	v_mul_f32_e32 v80, v105, v105
	v_fmac_f32_e32 v80, v104, v104
	v_fmac_f32_e32 v80, v106, v106
	v_cvt_pk_fp8_f32 v77, v106, v107 op_sel:[0,0,1]
	v_fmac_f32_e32 v80, v107, v107
	v_add_f32_e32 v13, v13, v80
	s_waitcnt vmcnt(43)
	v_cvt_pk_bf16_f32 v68, v108, v109
	v_cvt_pk_bf16_f32 v69, v110, v111
	v_cvt_pk_fp8_f32 v78, v108, v109
	v_mul_f32_e32 v80, v109, v109
	v_fmac_f32_e32 v80, v108, v108
	v_fmac_f32_e32 v80, v110, v110
	v_cvt_pk_fp8_f32 v78, v110, v111 op_sel:[0,0,1]
	v_fmac_f32_e32 v80, v111, v111
	v_add_f32_e32 v13, v13, v80
	s_waitcnt vmcnt(42)
; __device__ __forceinline__ unsigned cvt_pk_bf16(float lo, float hi) { unsigned r; asm("v_cvt_pk_bf16_f32 %0, %1, %2" : "=v"(r) : "v"(lo), "v"(hi)); return r; }
; __device__ __forceinline__ float wave_sum(float s, int) { s += dppf<0x128>(s); s += dppf<0x124>(s); s += dppf<0x122>(s); s += dppf<0x121>(s); return psum32(psum16(s)); }
; __device__ __forceinline__ void p0_prep(const Params& p, unsigned char* lds, int bid, int nb) {
;     ...
;     for (int row = bid * 8 + wid; row < T; row += nb * 8) {
;       const f32x4* src = (const f32x4*)(p.x + (size_t)row * D); float s = 0.f;
; #pragma unroll
;       for (int j = 0; j < 8; ++j) { const f32x4 v = src[lane + 64 * j]; s += v[0] * v[0] + v[1] * v[1] + v[2] * v[2] + v[3] * v[3];
;         u32x2 o; o[0] = cvt_pk_bf16(v[0], v[1]); o[1] = cvt_pk_bf16(v[2], v[3]); *(u32x2*)(xb + (size_t)row * D + (lane + 64 * j) * 4) = o;
;         unsigned q8 = __builtin_amdgcn_cvt_pk_fp8_f32(v[0], v[1], 0, false); q8 = __builtin_amdgcn_cvt_pk_fp8_f32(v[2], v[3], q8, true); *(unsigned*)(xq + (size_t)row * D + (lane + 64 * j) * 4) = q8; }
;       s = wave_sum(s, lane); if (lane == 0) ss0[row] = s;
;     }
	v_cvt_pk_bf16_f32 v70, v112, v113
	v_cvt_pk_bf16_f32 v71, v114, v115
	v_cvt_pk_fp8_f32 v79, v112, v113
	v_mul_f32_e32 v80, v113, v113
	v_fmac_f32_e32 v80, v112, v112
	v_fmac_f32_e32 v80, v114, v114
	v_cvt_pk_fp8_f32 v79, v114, v115 op_sel:[0,0,1]
	v_fmac_f32_e32 v80, v115, v115
	v_add_f32_e32 v13, v13, v80
	global_load_dwordx4 v[84:87], v[82:83], off offset:-4096
	global_load_dwordx4 v[88:91], v[82:83], off offset:-3072
	global_load_dwordx4 v[92:95], v[82:83], off offset:-2048
	global_load_dwordx4 v[96:99], v[82:83], off offset:-1024
	global_load_dwordx4 v[100:103], v[82:83], off
	global_load_dwordx4 v[104:107], v[82:83], off offset:1024
	global_load_dwordx4 v[108:111], v[82:83], off offset:2048
	global_load_dwordx4 v[112:115], v[82:83], off offset:3072
	v_lshl_add_u64 v[82:83], v[82:83], 0, s[16:17]
	global_store_dwordx2 v[8:9], v[56:57], off offset:-2048
	global_store_dword v[6:7], v72, off offset:-1024
	global_store_dwordx2 v[8:9], v[58:59], off offset:-1536
	global_store_dword v[6:7], v73, off offset:-768
	global_store_dwordx2 v[8:9], v[60:61], off offset:-1024
	global_store_dword v[6:7], v74, off offset:-512
	global_store_dwordx2 v[8:9], v[62:63], off offset:-512
	global_store_dword v[6:7], v75, off offset:-256
	global_store_dwordx2 v[8:9], v[64:65], off
	global_store_dword v[6:7], v76, off
	global_store_dwordx2 v[8:9], v[66:67], off offset:512
	global_store_dword v[6:7], v77, off offset:256
	global_store_dwordx2 v[8:9], v[68:69], off offset:1024
	global_store_dword v[6:7], v78, off offset:512
	global_store_dwordx2 v[8:9], v[70:71], off offset:1536
	global_store_dword v[6:7], v79, off offset:768
	v_add_f32_dpp v13, v13, v13 row_ror:8 row_mask:0xf bank_mask:0xf bound_ctrl:1
	s_nop 1
	v_add_f32_dpp v13, v13, v13 row_ror:4 row_mask:0xf bank_mask:0xf bound_ctrl:1
	s_nop 1
	v_add_f32_dpp v13, v13, v13 row_ror:2 row_mask:0xf bank_mask:0xf bound_ctrl:1
	s_nop 1
	v_add_f32_dpp v3, v13, v13 row_ror:1 row_mask:0xf bank_mask:0xf bound_ctrl:1
	v_mov_b32_e32 v13, v3
	s_nop 1
	v_permlane16_swap_b32_e32 v3, v13
	v_add_f32_e32 v3, v3, v13
	v_mov_b32_e32 v13, v3
	s_nop 1
	v_permlane32_swap_b32_e32 v3, v13
	s_and_saveexec_b64 s[4:5], vcc
	v_add_f32_e32 v3, v3, v13
	global_store_dword v[4:5], v3, off
	s_or_b64 exec, exec, s[4:5]
	v_lshl_add_u64 v[4:5], v[4:5], 0, s[10:11]
	v_lshl_add_u64 v[6:7], v[6:7], 0, s[12:13]
	v_lshl_add_u64 v[8:9], v[8:9], 0, s[14:15]
	s_waitcnt vmcnt(49)
	v_cvt_pk_bf16_f32 v56, v14, v15
	v_cvt_pk_bf16_f32 v57, v16, v17
	v_cvt_pk_fp8_f32 v72, v14, v15
	v_mul_f32_e32 v13, v15, v15
	v_fmac_f32_e32 v13, v14, v14
	v_fmac_f32_e32 v13, v16, v16
	v_cvt_pk_fp8_f32 v72, v16, v17 op_sel:[0,0,1]
	v_fmac_f32_e32 v13, v17, v17
	s_waitcnt vmcnt(48)
	v_cvt_pk_bf16_f32 v58, v18, v19
	v_cvt_pk_bf16_f32 v59, v20, v21
	v_cvt_pk_fp8_f32 v73, v18, v19
	v_mul_f32_e32 v80, v19, v19
	v_fmac_f32_e32 v80, v18, v18
	v_fmac_f32_e32 v80, v20, v20
	v_cvt_pk_fp8_f32 v73, v20, v21 op_sel:[0,0,1]
	v_fmac_f32_e32 v80, v21, v21
	v_add_f32_e32 v13, v13, v80
	s_waitcnt vmcnt(47)
	v_cvt_pk_bf16_f32 v60, v24, v25
	v_cvt_pk_bf16_f32 v61, v26, v27
	v_cvt_pk_fp8_f32 v74, v24, v25
	v_mul_f32_e32 v80, v25, v25
	v_fmac_f32_e32 v80, v24, v24
	v_fmac_f32_e32 v80, v26, v26
	v_cvt_pk_fp8_f32 v74, v26, v27 op_sel:[0,0,1]
	v_fmac_f32_e32 v80, v27, v27
	v_add_f32_e32 v13, v13, v80
	s_waitcnt vmcnt(46)
	v_cvt_pk_bf16_f32 v62, v28, v29
	v_cvt_pk_bf16_f32 v63, v30, v31
	v_cvt_pk_fp8_f32 v75, v28, v29
	v_mul_f32_e32 v80, v29, v29
	v_fmac_f32_e32 v80, v28, v28
	v_fmac_f32_e32 v80, v30, v30
	v_cvt_pk_fp8_f32 v75, v30, v31 op_sel:[0,0,1]
	v_fmac_f32_e32 v80, v31, v31
	v_add_f32_e32 v13, v13, v80
	s_waitcnt vmcnt(45)
	v_cvt_pk_bf16_f32 v64, v32, v33
	v_cvt_pk_bf16_f32 v65, v34, v35
	v_cvt_pk_fp8_f32 v76, v32, v33
	v_mul_f32_e32 v80, v33, v33
	v_fmac_f32_e32 v80, v32, v32
	v_fmac_f32_e32 v80, v34, v34
	v_cvt_pk_fp8_f32 v76, v34, v35 op_sel:[0,0,1]
	v_fmac_f32_e32 v80, v35, v35
	v_add_f32_e32 v13, v13, v80
	s_waitcnt vmcnt(44)
	v_cvt_pk_bf16_f32 v66, v36, v37
	v_cvt_pk_bf16_f32 v67, v38, v39
	v_cvt_pk_fp8_f32 v77, v36, v37
	v_mul_f32_e32 v80, v37, v37
	v_fmac_f32_e32 v80, v36, v36
	v_fmac_f32_e32 v80, v38, v38
	v_cvt_pk_fp8_f32 v77, v38, v39 op_sel:[0,0,1]
	v_fmac_f32_e32 v80, v39, v39
	v_add_f32_e32 v13, v13, v80
	s_waitcnt vmcnt(43)
	v_cvt_pk_bf16_f32 v68, v40, v41
	v_cvt_pk_bf16_f32 v69, v42, v43
	v_cvt_pk_fp8_f32 v78, v40, v41
	v_mul_f32_e32 v80, v41, v41
	v_fmac_f32_e32 v80, v40, v40
	v_fmac_f32_e32 v80, v42, v42
	v_cvt_pk_fp8_f32 v78, v42, v43 op_sel:[0,0,1]
	v_fmac_f32_e32 v80, v43, v43
	v_add_f32_e32 v13, v13, v80
	s_waitcnt vmcnt(42)
; __device__ __forceinline__ unsigned cvt_pk_bf16(float lo, float hi) { unsigned r; asm("v_cvt_pk_bf16_f32 %0, %1, %2" : "=v"(r) : "v"(lo), "v"(hi)); return r; }
; __device__ __forceinline__ float wave_sum(float s, int) { s += dppf<0x128>(s); s += dppf<0x124>(s); s += dppf<0x122>(s); s += dppf<0x121>(s); return psum32(psum16(s)); }
; __device__ __forceinline__ void p0_prep(const Params& p, unsigned char* lds, int bid, int nb) {
;     ...
;     for (int row = bid * 8 + wid; row < T; row += nb * 8) {
;       const f32x4* src = (const f32x4*)(p.x + (size_t)row * D); float s = 0.f;
; #pragma unroll
;       for (int j = 0; j < 8; ++j) { const f32x4 v = src[lane + 64 * j]; s += v[0] * v[0] + v[1] * v[1] + v[2] * v[2] + v[3] * v[3];
;         u32x2 o; o[0] = cvt_pk_bf16(v[0], v[1]); o[1] = cvt_pk_bf16(v[2], v[3]); *(u32x2*)(xb + (size_t)row * D + (lane + 64 * j) * 4) = o;
;         unsigned q8 = __builtin_amdgcn_cvt_pk_fp8_f32(v[0], v[1], 0, false); q8 = __builtin_amdgcn_cvt_pk_fp8_f32(v[2], v[3], q8, true); *(unsigned*)(xq + (size_t)row * D + (lane + 64 * j) * 4) = q8; }
;       s = wave_sum(s, lane); if (lane == 0) ss0[row] = s;
;     }
	v_cvt_pk_bf16_f32 v70, v44, v45
	v_cvt_pk_bf16_f32 v71, v46, v47
	v_cvt_pk_fp8_f32 v79, v44, v45
	v_mul_f32_e32 v80, v45, v45
	v_fmac_f32_e32 v80, v44, v44
	v_fmac_f32_e32 v80, v46, v46
	v_cvt_pk_fp8_f32 v79, v46, v47 op_sel:[0,0,1]
	v_fmac_f32_e32 v80, v47, v47
	v_add_f32_e32 v13, v13, v80
	global_load_dwordx4 v[14:17], v[82:83], off offset:-4096
	global_load_dwordx4 v[18:21], v[82:83], off offset:-3072
	global_load_dwordx4 v[24:27], v[82:83], off offset:-2048
	global_load_dwordx4 v[28:31], v[82:83], off offset:-1024
	global_load_dwordx4 v[32:35], v[82:83], off
	global_load_dwordx4 v[36:39], v[82:83], off offset:1024
	global_load_dwordx4 v[40:43], v[82:83], off offset:2048
	global_load_dwordx4 v[44:47], v[82:83], off offset:3072
	v_lshl_add_u64 v[82:83], v[82:83], 0, s[16:17]
	global_store_dwordx2 v[8:9], v[56:57], off offset:-2048
	global_store_dword v[6:7], v72, off offset:-1024
	global_store_dwordx2 v[8:9], v[58:59], off offset:-1536
	global_store_dword v[6:7], v73, off offset:-768
	global_store_dwordx2 v[8:9], v[60:61], off offset:-1024
	global_store_dword v[6:7], v74, off offset:-512
	global_store_dwordx2 v[8:9], v[62:63], off offset:-512
	global_store_dword v[6:7], v75, off offset:-256
	global_store_dwordx2 v[8:9], v[64:65], off
	global_store_dword v[6:7], v76, off
	global_store_dwordx2 v[8:9], v[66:67], off offset:512
	global_store_dword v[6:7], v77, off offset:256
	global_store_dwordx2 v[8:9], v[68:69], off offset:1024
	global_store_dword v[6:7], v78, off offset:512
	global_store_dwordx2 v[8:9], v[70:71], off offset:1536
	global_store_dword v[6:7], v79, off offset:768
	v_add_f32_dpp v13, v13, v13 row_ror:8 row_mask:0xf bank_mask:0xf bound_ctrl:1
	s_nop 1
	v_add_f32_dpp v13, v13, v13 row_ror:4 row_mask:0xf bank_mask:0xf bound_ctrl:1
	s_nop 1
	v_add_f32_dpp v13, v13, v13 row_ror:2 row_mask:0xf bank_mask:0xf bound_ctrl:1
	s_nop 1
	v_add_f32_dpp v3, v13, v13 row_ror:1 row_mask:0xf bank_mask:0xf bound_ctrl:1
	v_mov_b32_e32 v13, v3
	s_nop 1
	v_permlane16_swap_b32_e32 v3, v13
	v_add_f32_e32 v3, v3, v13
	v_mov_b32_e32 v13, v3
	s_nop 1
	v_permlane32_swap_b32_e32 v3, v13
	s_and_saveexec_b64 s[4:5], vcc
	v_add_f32_e32 v3, v3, v13
	global_store_dword v[4:5], v3, off
	s_or_b64 exec, exec, s[4:5]
	v_lshl_add_u64 v[4:5], v[4:5], 0, s[10:11]
	v_lshl_add_u64 v[6:7], v[6:7], 0, s[12:13]
	v_lshl_add_u64 v[8:9], v[8:9], 0, s[14:15]
	s_waitcnt vmcnt(49)
	v_cvt_pk_bf16_f32 v56, v84, v85
	v_cvt_pk_bf16_f32 v57, v86, v87
	v_cvt_pk_fp8_f32 v72, v84, v85
	v_mul_f32_e32 v13, v85, v85
	v_fmac_f32_e32 v13, v84, v84
	v_fmac_f32_e32 v13, v86, v86
	v_cvt_pk_fp8_f32 v72, v86, v87 op_sel:[0,0,1]
	v_fmac_f32_e32 v13, v87, v87
	s_waitcnt vmcnt(48)
	v_cvt_pk_bf16_f32 v58, v88, v89
	v_cvt_pk_bf16_f32 v59, v90, v91
	v_cvt_pk_fp8_f32 v73, v88, v89
	v_mul_f32_e32 v80, v89, v89
	v_fmac_f32_e32 v80, v88, v88
	v_fmac_f32_e32 v80, v90, v90
	v_cvt_pk_fp8_f32 v73, v90, v91 op_sel:[0,0,1]
	v_fmac_f32_e32 v80, v91, v91
	v_add_f32_e32 v13, v13, v80
	s_waitcnt vmcnt(47)
	v_cvt_pk_bf16_f32 v60, v92, v93
	v_cvt_pk_bf16_f32 v61, v94, v95
	v_cvt_pk_fp8_f32 v74, v92, v93
	v_mul_f32_e32 v80, v93, v93
	v_fmac_f32_e32 v80, v92, v92
	v_fmac_f32_e32 v80, v94, v94
	v_cvt_pk_fp8_f32 v74, v94, v95 op_sel:[0,0,1]
	v_fmac_f32_e32 v80, v95, v95
	v_add_f32_e32 v13, v13, v80
	s_waitcnt vmcnt(46)
	v_cvt_pk_bf16_f32 v62, v96, v97
	v_cvt_pk_bf16_f32 v63, v98, v99
	v_cvt_pk_fp8_f32 v75, v96, v97
	v_mul_f32_e32 v80, v97, v97
	v_fmac_f32_e32 v80, v96, v96
	v_fmac_f32_e32 v80, v98, v98
	v_cvt_pk_fp8_f32 v75, v98, v99 op_sel:[0,0,1]
	v_fmac_f32_e32 v80, v99, v99
	v_add_f32_e32 v13, v13, v80
	s_waitcnt vmcnt(45)
	v_cvt_pk_bf16_f32 v64, v100, v101
	v_cvt_pk_bf16_f32 v65, v102, v103
	v_cvt_pk_fp8_f32 v76, v100, v101
	v_mul_f32_e32 v80, v101, v101
	v_fmac_f32_e32 v80, v100, v100
	v_fmac_f32_e32 v80, v102, v102
	v_cvt_pk_fp8_f32 v76, v102, v103 op_sel:[0,0,1]
	v_fmac_f32_e32 v80, v103, v103
	v_add_f32_e32 v13, v13, v80
	s_waitcnt vmcnt(44)
	v_cvt_pk_bf16_f32 v66, v104, v105
	v_cvt_pk_bf16_f32 v67, v106, v107
	v_cvt_pk_fp8_f32 v77, v104, v105
	v_mul_f32_e32 v80, v105, v105
	v_fmac_f32_e32 v80, v104, v104
	v_fmac_f32_e32 v80, v106, v106
	v_cvt_pk_fp8_f32 v77, v106, v107 op_sel:[0,0,1]
	v_fmac_f32_e32 v80, v107, v107
	v_add_f32_e32 v13, v13, v80
	s_waitcnt vmcnt(43)
	v_cvt_pk_bf16_f32 v68, v108, v109
	v_cvt_pk_bf16_f32 v69, v110, v111
	v_cvt_pk_fp8_f32 v78, v108, v109
	v_mul_f32_e32 v80, v109, v109
	v_fmac_f32_e32 v80, v108, v108
	v_fmac_f32_e32 v80, v110, v110
	v_cvt_pk_fp8_f32 v78, v110, v111 op_sel:[0,0,1]
	v_fmac_f32_e32 v80, v111, v111
	v_add_f32_e32 v13, v13, v80
	s_waitcnt vmcnt(42)
; __device__ __forceinline__ unsigned cvt_pk_bf16(float lo, float hi) { unsigned r; asm("v_cvt_pk_bf16_f32 %0, %1, %2" : "=v"(r) : "v"(lo), "v"(hi)); return r; }
; __device__ __forceinline__ float wave_sum(float s, int) { s += dppf<0x128>(s); s += dppf<0x124>(s); s += dppf<0x122>(s); s += dppf<0x121>(s); return psum32(psum16(s)); }
; __device__ __forceinline__ void p0_prep(const Params& p, unsigned char* lds, int bid, int nb) {
;     ...
;     for (int row = bid * 8 + wid; row < T; row += nb * 8) {
;       const f32x4* src = (const f32x4*)(p.x + (size_t)row * D); float s = 0.f;
; #pragma unroll
;       for (int j = 0; j < 8; ++j) { const f32x4 v = src[lane + 64 * j]; s += v[0] * v[0] + v[1] * v[1] + v[2] * v[2] + v[3] * v[3];
;         u32x2 o; o[0] = cvt_pk_bf16(v[0], v[1]); o[1] = cvt_pk_bf16(v[2], v[3]); *(u32x2*)(xb + (size_t)row * D + (lane + 64 * j) * 4) = o;
;         unsigned q8 = __builtin_amdgcn_cvt_pk_fp8_f32(v[0], v[1], 0, false); q8 = __builtin_amdgcn_cvt_pk_fp8_f32(v[2], v[3], q8, true); *(unsigned*)(xq + (size_t)row * D + (lane + 64 * j) * 4) = q8; }
;       s = wave_sum(s, lane); if (lane == 0) ss0[row] = s;
;     }
	v_cvt_pk_bf16_f32 v70, v112, v113
	v_cvt_pk_bf16_f32 v71, v114, v115
	v_cvt_pk_fp8_f32 v79, v112, v113
	v_mul_f32_e32 v80, v113, v113
	v_fmac_f32_e32 v80, v112, v112
	v_fmac_f32_e32 v80, v114, v114
	v_cvt_pk_fp8_f32 v79, v114, v115 op_sel:[0,0,1]
	v_fmac_f32_e32 v80, v115, v115
	v_add_f32_e32 v13, v13, v80
	global_load_dwordx4 v[84:87], v[82:83], off offset:-4096
	global_load_dwordx4 v[88:91], v[82:83], off offset:-3072
	global_load_dwordx4 v[92:95], v[82:83], off offset:-2048
	global_load_dwordx4 v[96:99], v[82:83], off offset:-1024
	global_load_dwordx4 v[100:103], v[82:83], off
	global_load_dwordx4 v[104:107], v[82:83], off offset:1024
	global_load_dwordx4 v[108:111], v[82:83], off offset:2048
	global_load_dwordx4 v[112:115], v[82:83], off offset:3072
	v_lshl_add_u64 v[82:83], v[82:83], 0, s[16:17]
	global_store_dwordx2 v[8:9], v[56:57], off offset:-2048
	global_store_dword v[6:7], v72, off offset:-1024
	global_store_dwordx2 v[8:9], v[58:59], off offset:-1536
	global_store_dword v[6:7], v73, off offset:-768
	global_store_dwordx2 v[8:9], v[60:61], off offset:-1024
	global_store_dword v[6:7], v74, off offset:-512
	global_store_dwordx2 v[8:9], v[62:63], off offset:-512
	global_store_dword v[6:7], v75, off offset:-256
	global_store_dwordx2 v[8:9], v[64:65], off
	global_store_dword v[6:7], v76, off
	global_store_dwordx2 v[8:9], v[66:67], off offset:512
	global_store_dword v[6:7], v77, off offset:256
	global_store_dwordx2 v[8:9], v[68:69], off offset:1024
	global_store_dword v[6:7], v78, off offset:512
	global_store_dwordx2 v[8:9], v[70:71], off offset:1536
	global_store_dword v[6:7], v79, off offset:768
	v_add_f32_dpp v13, v13, v13 row_ror:8 row_mask:0xf bank_mask:0xf bound_ctrl:1
	s_nop 1
	v_add_f32_dpp v13, v13, v13 row_ror:4 row_mask:0xf bank_mask:0xf bound_ctrl:1
	s_nop 1
	v_add_f32_dpp v13, v13, v13 row_ror:2 row_mask:0xf bank_mask:0xf bound_ctrl:1
	s_nop 1
	v_add_f32_dpp v3, v13, v13 row_ror:1 row_mask:0xf bank_mask:0xf bound_ctrl:1
	v_mov_b32_e32 v13, v3
	s_nop 1
	v_permlane16_swap_b32_e32 v3, v13
	v_add_f32_e32 v3, v3, v13
	v_mov_b32_e32 v13, v3
	s_nop 1
	v_permlane32_swap_b32_e32 v3, v13
	s_and_saveexec_b64 s[4:5], vcc
	v_add_f32_e32 v3, v3, v13
	global_store_dword v[4:5], v3, off
	s_or_b64 exec, exec, s[4:5]
	v_lshl_add_u64 v[4:5], v[4:5], 0, s[10:11]
	v_lshl_add_u64 v[6:7], v[6:7], 0, s[12:13]
	v_lshl_add_u64 v[8:9], v[8:9], 0, s[14:15]
	s_waitcnt vmcnt(49)
	v_cvt_pk_bf16_f32 v56, v14, v15
	v_cvt_pk_bf16_f32 v57, v16, v17
	v_cvt_pk_fp8_f32 v72, v14, v15
	v_mul_f32_e32 v13, v15, v15
	v_fmac_f32_e32 v13, v14, v14
	v_fmac_f32_e32 v13, v16, v16
	v_cvt_pk_fp8_f32 v72, v16, v17 op_sel:[0,0,1]
	v_fmac_f32_e32 v13, v17, v17
	s_waitcnt vmcnt(48)
	v_cvt_pk_bf16_f32 v58, v18, v19
	v_cvt_pk_bf16_f32 v59, v20, v21
	v_cvt_pk_fp8_f32 v73, v18, v19
	v_mul_f32_e32 v80, v19, v19
	v_fmac_f32_e32 v80, v18, v18
	v_fmac_f32_e32 v80, v20, v20
	v_cvt_pk_fp8_f32 v73, v20, v21 op_sel:[0,0,1]
	v_fmac_f32_e32 v80, v21, v21
	v_add_f32_e32 v13, v13, v80
	s_waitcnt vmcnt(47)
	v_cvt_pk_bf16_f32 v60, v24, v25
	v_cvt_pk_bf16_f32 v61, v26, v27
	v_cvt_pk_fp8_f32 v74, v24, v25
	v_mul_f32_e32 v80, v25, v25
	v_fmac_f32_e32 v80, v24, v24
	v_fmac_f32_e32 v80, v26, v26
	v_cvt_pk_fp8_f32 v74, v26, v27 op_sel:[0,0,1]
	v_fmac_f32_e32 v80, v27, v27
	v_add_f32_e32 v13, v13, v80
	s_waitcnt vmcnt(46)
	v_cvt_pk_bf16_f32 v62, v28, v29
	v_cvt_pk_bf16_f32 v63, v30, v31
	v_cvt_pk_fp8_f32 v75, v28, v29
	v_mul_f32_e32 v80, v29, v29
	v_fmac_f32_e32 v80, v28, v28
	v_fmac_f32_e32 v80, v30, v30
	v_cvt_pk_fp8_f32 v75, v30, v31 op_sel:[0,0,1]
	v_fmac_f32_e32 v80, v31, v31
	v_add_f32_e32 v13, v13, v80
	s_waitcnt vmcnt(45)
	v_cvt_pk_bf16_f32 v64, v32, v33
	v_cvt_pk_bf16_f32 v65, v34, v35
	v_cvt_pk_fp8_f32 v76, v32, v33
	v_mul_f32_e32 v80, v33, v33
	v_fmac_f32_e32 v80, v32, v32
	v_fmac_f32_e32 v80, v34, v34
	v_cvt_pk_fp8_f32 v76, v34, v35 op_sel:[0,0,1]
	v_fmac_f32_e32 v80, v35, v35
	v_add_f32_e32 v13, v13, v80
	s_waitcnt vmcnt(44)
	v_cvt_pk_bf16_f32 v66, v36, v37
	v_cvt_pk_bf16_f32 v67, v38, v39
	v_cvt_pk_fp8_f32 v77, v36, v37
	v_mul_f32_e32 v80, v37, v37
	v_fmac_f32_e32 v80, v36, v36
	v_fmac_f32_e32 v80, v38, v38
	v_cvt_pk_fp8_f32 v77, v38, v39 op_sel:[0,0,1]
	v_fmac_f32_e32 v80, v39, v39
	v_add_f32_e32 v13, v13, v80
	s_waitcnt vmcnt(43)
	v_cvt_pk_bf16_f32 v68, v40, v41
	v_cvt_pk_bf16_f32 v69, v42, v43
	v_cvt_pk_fp8_f32 v78, v40, v41
	v_mul_f32_e32 v80, v41, v41
	v_fmac_f32_e32 v80, v40, v40
	v_fmac_f32_e32 v80, v42, v42
	v_cvt_pk_fp8_f32 v78, v42, v43 op_sel:[0,0,1]
	v_fmac_f32_e32 v80, v43, v43
	v_add_f32_e32 v13, v13, v80
	s_waitcnt vmcnt(42)
; __device__ __forceinline__ unsigned cvt_pk_bf16(float lo, float hi) { unsigned r; asm("v_cvt_pk_bf16_f32 %0, %1, %2" : "=v"(r) : "v"(lo), "v"(hi)); return r; }
; __device__ __forceinline__ float wave_sum(float s, int) { s += dppf<0x128>(s); s += dppf<0x124>(s); s += dppf<0x122>(s); s += dppf<0x121>(s); return psum32(psum16(s)); }
; __device__ __forceinline__ void p0_prep(const Params& p, unsigned char* lds, int bid, int nb) {
;     ...
;     for (int row = bid * 8 + wid; row < T; row += nb * 8) {
;       const f32x4* src = (const f32x4*)(p.x + (size_t)row * D); float s = 0.f;
; #pragma unroll
;       for (int j = 0; j < 8; ++j) { const f32x4 v = src[lane + 64 * j]; s += v[0] * v[0] + v[1] * v[1] + v[2] * v[2] + v[3] * v[3];
;         u32x2 o; o[0] = cvt_pk_bf16(v[0], v[1]); o[1] = cvt_pk_bf16(v[2], v[3]); *(u32x2*)(xb + (size_t)row * D + (lane + 64 * j) * 4) = o;
;         unsigned q8 = __builtin_amdgcn_cvt_pk_fp8_f32(v[0], v[1], 0, false); q8 = __builtin_amdgcn_cvt_pk_fp8_f32(v[2], v[3], q8, true); *(unsigned*)(xq + (size_t)row * D + (lane + 64 * j) * 4) = q8; }
;       s = wave_sum(s, lane); if (lane == 0) ss0[row] = s;
;     }
	v_cvt_pk_bf16_f32 v70, v44, v45
	v_cvt_pk_bf16_f32 v71, v46, v47
	v_cvt_pk_fp8_f32 v79, v44, v45
	v_mul_f32_e32 v80, v45, v45
	v_fmac_f32_e32 v80, v44, v44
	v_fmac_f32_e32 v80, v46, v46
	v_cvt_pk_fp8_f32 v79, v46, v47 op_sel:[0,0,1]
	v_fmac_f32_e32 v80, v47, v47
	v_add_f32_e32 v13, v13, v80
	global_load_dwordx4 v[14:17], v[82:83], off offset:-4096
	global_load_dwordx4 v[18:21], v[82:83], off offset:-3072
	global_load_dwordx4 v[24:27], v[82:83], off offset:-2048
	global_load_dwordx4 v[28:31], v[82:83], off offset:-1024
	global_load_dwordx4 v[32:35], v[82:83], off
	global_load_dwordx4 v[36:39], v[82:83], off offset:1024
	global_load_dwordx4 v[40:43], v[82:83], off offset:2048
	global_load_dwordx4 v[44:47], v[82:83], off offset:3072
	v_lshl_add_u64 v[82:83], v[82:83], 0, s[16:17]
	global_store_dwordx2 v[8:9], v[56:57], off offset:-2048
	global_store_dword v[6:7], v72, off offset:-1024
	global_store_dwordx2 v[8:9], v[58:59], off offset:-1536
	global_store_dword v[6:7], v73, off offset:-768
	global_store_dwordx2 v[8:9], v[60:61], off offset:-1024
	global_store_dword v[6:7], v74, off offset:-512
	global_store_dwordx2 v[8:9], v[62:63], off offset:-512
	global_store_dword v[6:7], v75, off offset:-256
	global_store_dwordx2 v[8:9], v[64:65], off
	global_store_dword v[6:7], v76, off
	global_store_dwordx2 v[8:9], v[66:67], off offset:512
	global_store_dword v[6:7], v77, off offset:256
	global_store_dwordx2 v[8:9], v[68:69], off offset:1024
	global_store_dword v[6:7], v78, off offset:512
	global_store_dwordx2 v[8:9], v[70:71], off offset:1536
	global_store_dword v[6:7], v79, off offset:768
	v_add_f32_dpp v13, v13, v13 row_ror:8 row_mask:0xf bank_mask:0xf bound_ctrl:1
	s_nop 1
	v_add_f32_dpp v13, v13, v13 row_ror:4 row_mask:0xf bank_mask:0xf bound_ctrl:1
	s_nop 1
	v_add_f32_dpp v13, v13, v13 row_ror:2 row_mask:0xf bank_mask:0xf bound_ctrl:1
	s_nop 1
	v_add_f32_dpp v3, v13, v13 row_ror:1 row_mask:0xf bank_mask:0xf bound_ctrl:1
	v_mov_b32_e32 v13, v3
	s_nop 1
	v_permlane16_swap_b32_e32 v3, v13
	v_add_f32_e32 v3, v3, v13
	v_mov_b32_e32 v13, v3
	s_nop 1
	v_permlane32_swap_b32_e32 v3, v13
	s_and_saveexec_b64 s[4:5], vcc
	v_add_f32_e32 v3, v3, v13
	global_store_dword v[4:5], v3, off
	s_or_b64 exec, exec, s[4:5]
	v_lshl_add_u64 v[4:5], v[4:5], 0, s[10:11]
	v_lshl_add_u64 v[6:7], v[6:7], 0, s[12:13]
	v_lshl_add_u64 v[8:9], v[8:9], 0, s[14:15]
	s_waitcnt vmcnt(49)
	v_cvt_pk_bf16_f32 v56, v84, v85
	v_cvt_pk_bf16_f32 v57, v86, v87
	v_cvt_pk_fp8_f32 v72, v84, v85
	v_mul_f32_e32 v13, v85, v85
	v_fmac_f32_e32 v13, v84, v84
	v_fmac_f32_e32 v13, v86, v86
	v_cvt_pk_fp8_f32 v72, v86, v87 op_sel:[0,0,1]
	v_fmac_f32_e32 v13, v87, v87
	s_waitcnt vmcnt(48)
	v_cvt_pk_bf16_f32 v58, v88, v89
	v_cvt_pk_bf16_f32 v59, v90, v91
	v_cvt_pk_fp8_f32 v73, v88, v89
	v_mul_f32_e32 v80, v89, v89
	v_fmac_f32_e32 v80, v88, v88
	v_fmac_f32_e32 v80, v90, v90
	v_cvt_pk_fp8_f32 v73, v90, v91 op_sel:[0,0,1]
	v_fmac_f32_e32 v80, v91, v91
	v_add_f32_e32 v13, v13, v80
	s_waitcnt vmcnt(47)
	v_cvt_pk_bf16_f32 v60, v92, v93
	v_cvt_pk_bf16_f32 v61, v94, v95
	v_cvt_pk_fp8_f32 v74, v92, v93
	v_mul_f32_e32 v80, v93, v93
	v_fmac_f32_e32 v80, v92, v92
	v_fmac_f32_e32 v80, v94, v94
	v_cvt_pk_fp8_f32 v74, v94, v95 op_sel:[0,0,1]
	v_fmac_f32_e32 v80, v95, v95
	v_add_f32_e32 v13, v13, v80
	s_waitcnt vmcnt(46)
	v_cvt_pk_bf16_f32 v62, v96, v97
	v_cvt_pk_bf16_f32 v63, v98, v99
	v_cvt_pk_fp8_f32 v75, v96, v97
	v_mul_f32_e32 v80, v97, v97
	v_fmac_f32_e32 v80, v96, v96
	v_fmac_f32_e32 v80, v98, v98
	v_cvt_pk_fp8_f32 v75, v98, v99 op_sel:[0,0,1]
	v_fmac_f32_e32 v80, v99, v99
	v_add_f32_e32 v13, v13, v80
	s_waitcnt vmcnt(45)
	v_cvt_pk_bf16_f32 v64, v100, v101
	v_cvt_pk_bf16_f32 v65, v102, v103
	v_cvt_pk_fp8_f32 v76, v100, v101
	v_mul_f32_e32 v80, v101, v101
	v_fmac_f32_e32 v80, v100, v100
	v_fmac_f32_e32 v80, v102, v102
	v_cvt_pk_fp8_f32 v76, v102, v103 op_sel:[0,0,1]
	v_fmac_f32_e32 v80, v103, v103
	v_add_f32_e32 v13, v13, v80
	s_waitcnt vmcnt(44)
	v_cvt_pk_bf16_f32 v66, v104, v105
	v_cvt_pk_bf16_f32 v67, v106, v107
	v_cvt_pk_fp8_f32 v77, v104, v105
	v_mul_f32_e32 v80, v105, v105
	v_fmac_f32_e32 v80, v104, v104
	v_fmac_f32_e32 v80, v106, v106
	v_cvt_pk_fp8_f32 v77, v106, v107 op_sel:[0,0,1]
	v_fmac_f32_e32 v80, v107, v107
	v_add_f32_e32 v13, v13, v80
	s_waitcnt vmcnt(43)
	v_cvt_pk_bf16_f32 v68, v108, v109
	v_cvt_pk_bf16_f32 v69, v110, v111
	v_cvt_pk_fp8_f32 v78, v108, v109
	v_mul_f32_e32 v80, v109, v109
	v_fmac_f32_e32 v80, v108, v108
	v_fmac_f32_e32 v80, v110, v110
	v_cvt_pk_fp8_f32 v78, v110, v111 op_sel:[0,0,1]
	v_fmac_f32_e32 v80, v111, v111
	v_add_f32_e32 v13, v13, v80
	s_waitcnt vmcnt(42)
; __device__ __forceinline__ unsigned cvt_pk_bf16(float lo, float hi) { unsigned r; asm("v_cvt_pk_bf16_f32 %0, %1, %2" : "=v"(r) : "v"(lo), "v"(hi)); return r; }
; __device__ __forceinline__ float wave_sum(float s, int) { s += dppf<0x128>(s); s += dppf<0x124>(s); s += dppf<0x122>(s); s += dppf<0x121>(s); return psum32(psum16(s)); }
; __device__ __forceinline__ void p0_prep(const Params& p, unsigned char* lds, int bid, int nb) {
;     ...
;     for (int row = bid * 8 + wid; row < T; row += nb * 8) {
;       const f32x4* src = (const f32x4*)(p.x + (size_t)row * D); float s = 0.f;
; #pragma unroll
;       for (int j = 0; j < 8; ++j) { const f32x4 v = src[lane + 64 * j]; s += v[0] * v[0] + v[1] * v[1] + v[2] * v[2] + v[3] * v[3];
;         u32x2 o; o[0] = cvt_pk_bf16(v[0], v[1]); o[1] = cvt_pk_bf16(v[2], v[3]); *(u32x2*)(xb + (size_t)row * D + (lane + 64 * j) * 4) = o;
;         unsigned q8 = __builtin_amdgcn_cvt_pk_fp8_f32(v[0], v[1], 0, false); q8 = __builtin_amdgcn_cvt_pk_fp8_f32(v[2], v[3], q8, true); *(unsigned*)(xq + (size_t)row * D + (lane + 64 * j) * 4) = q8; }
;       s = wave_sum(s, lane); if (lane == 0) ss0[row] = s;
;     }
	v_cvt_pk_bf16_f32 v70, v112, v113
	v_cvt_pk_bf16_f32 v71, v114, v115
	v_cvt_pk_fp8_f32 v79, v112, v113
	v_mul_f32_e32 v80, v113, v113
	v_fmac_f32_e32 v80, v112, v112
	v_fmac_f32_e32 v80, v114, v114
	v_cvt_pk_fp8_f32 v79, v114, v115 op_sel:[0,0,1]
	v_fmac_f32_e32 v80, v115, v115
	v_add_f32_e32 v13, v13, v80
	global_load_dwordx4 v[84:87], v[82:83], off offset:-4096
	global_load_dwordx4 v[88:91], v[82:83], off offset:-3072
	global_load_dwordx4 v[92:95], v[82:83], off offset:-2048
	global_load_dwordx4 v[96:99], v[82:83], off offset:-1024
	global_load_dwordx4 v[100:103], v[82:83], off
	global_load_dwordx4 v[104:107], v[82:83], off offset:1024
	global_load_dwordx4 v[108:111], v[82:83], off offset:2048
	global_load_dwordx4 v[112:115], v[82:83], off offset:3072
	v_lshl_add_u64 v[82:83], v[82:83], 0, s[16:17]
	global_store_dwordx2 v[8:9], v[56:57], off offset:-2048
	global_store_dword v[6:7], v72, off offset:-1024
	global_store_dwordx2 v[8:9], v[58:59], off offset:-1536
	global_store_dword v[6:7], v73, off offset:-768
	global_store_dwordx2 v[8:9], v[60:61], off offset:-1024
	global_store_dword v[6:7], v74, off offset:-512
	global_store_dwordx2 v[8:9], v[62:63], off offset:-512
	global_store_dword v[6:7], v75, off offset:-256
	global_store_dwordx2 v[8:9], v[64:65], off
	global_store_dword v[6:7], v76, off
	global_store_dwordx2 v[8:9], v[66:67], off offset:512
	global_store_dword v[6:7], v77, off offset:256
	global_store_dwordx2 v[8:9], v[68:69], off offset:1024
	global_store_dword v[6:7], v78, off offset:512
	global_store_dwordx2 v[8:9], v[70:71], off offset:1536
	global_store_dword v[6:7], v79, off offset:768
	v_add_f32_dpp v13, v13, v13 row_ror:8 row_mask:0xf bank_mask:0xf bound_ctrl:1
	s_nop 1
	v_add_f32_dpp v13, v13, v13 row_ror:4 row_mask:0xf bank_mask:0xf bound_ctrl:1
	s_nop 1
	v_add_f32_dpp v13, v13, v13 row_ror:2 row_mask:0xf bank_mask:0xf bound_ctrl:1
	s_nop 1
	v_add_f32_dpp v3, v13, v13 row_ror:1 row_mask:0xf bank_mask:0xf bound_ctrl:1
	v_mov_b32_e32 v13, v3
	s_nop 1
	v_permlane16_swap_b32_e32 v3, v13
	v_add_f32_e32 v3, v3, v13
	v_mov_b32_e32 v13, v3
	s_nop 1
	v_permlane32_swap_b32_e32 v3, v13
	s_and_saveexec_b64 s[4:5], vcc
	v_add_f32_e32 v3, v3, v13
	global_store_dword v[4:5], v3, off
	s_or_b64 exec, exec, s[4:5]
	v_lshl_add_u64 v[4:5], v[4:5], 0, s[10:11]
	v_lshl_add_u64 v[6:7], v[6:7], 0, s[12:13]
	v_lshl_add_u64 v[8:9], v[8:9], 0, s[14:15]
	s_waitcnt vmcnt(49)
	v_cvt_pk_bf16_f32 v56, v14, v15
	v_cvt_pk_bf16_f32 v57, v16, v17
	v_cvt_pk_fp8_f32 v72, v14, v15
	v_mul_f32_e32 v13, v15, v15
	v_fmac_f32_e32 v13, v14, v14
	v_fmac_f32_e32 v13, v16, v16
	v_cvt_pk_fp8_f32 v72, v16, v17 op_sel:[0,0,1]
	v_fmac_f32_e32 v13, v17, v17
	s_waitcnt vmcnt(48)
	v_cvt_pk_bf16_f32 v58, v18, v19
	v_cvt_pk_bf16_f32 v59, v20, v21
	v_cvt_pk_fp8_f32 v73, v18, v19
	v_mul_f32_e32 v80, v19, v19
	v_fmac_f32_e32 v80, v18, v18
	v_fmac_f32_e32 v80, v20, v20
	v_cvt_pk_fp8_f32 v73, v20, v21 op_sel:[0,0,1]
	v_fmac_f32_e32 v80, v21, v21
	v_add_f32_e32 v13, v13, v80
	s_waitcnt vmcnt(47)
	v_cvt_pk_bf16_f32 v60, v24, v25
	v_cvt_pk_bf16_f32 v61, v26, v27
	v_cvt_pk_fp8_f32 v74, v24, v25
	v_mul_f32_e32 v80, v25, v25
	v_fmac_f32_e32 v80, v24, v24
	v_fmac_f32_e32 v80, v26, v26
	v_cvt_pk_fp8_f32 v74, v26, v27 op_sel:[0,0,1]
	v_fmac_f32_e32 v80, v27, v27
	v_add_f32_e32 v13, v13, v80
	s_waitcnt vmcnt(46)
	v_cvt_pk_bf16_f32 v62, v28, v29
	v_cvt_pk_bf16_f32 v63, v30, v31
	v_cvt_pk_fp8_f32 v75, v28, v29
	v_mul_f32_e32 v80, v29, v29
	v_fmac_f32_e32 v80, v28, v28
	v_fmac_f32_e32 v80, v30, v30
	v_cvt_pk_fp8_f32 v75, v30, v31 op_sel:[0,0,1]
	v_fmac_f32_e32 v80, v31, v31
	v_add_f32_e32 v13, v13, v80
	s_waitcnt vmcnt(45)
	v_cvt_pk_bf16_f32 v64, v32, v33
	v_cvt_pk_bf16_f32 v65, v34, v35
	v_cvt_pk_fp8_f32 v76, v32, v33
	v_mul_f32_e32 v80, v33, v33
	v_fmac_f32_e32 v80, v32, v32
	v_fmac_f32_e32 v80, v34, v34
	v_cvt_pk_fp8_f32 v76, v34, v35 op_sel:[0,0,1]
	v_fmac_f32_e32 v80, v35, v35
	v_add_f32_e32 v13, v13, v80
	s_waitcnt vmcnt(44)
	v_cvt_pk_bf16_f32 v66, v36, v37
	v_cvt_pk_bf16_f32 v67, v38, v39
	v_cvt_pk_fp8_f32 v77, v36, v37
	v_mul_f32_e32 v80, v37, v37
	v_fmac_f32_e32 v80, v36, v36
	v_fmac_f32_e32 v80, v38, v38
	v_cvt_pk_fp8_f32 v77, v38, v39 op_sel:[0,0,1]
	v_fmac_f32_e32 v80, v39, v39
	v_add_f32_e32 v13, v13, v80
	s_waitcnt vmcnt(43)
	v_cvt_pk_bf16_f32 v68, v40, v41
	v_cvt_pk_bf16_f32 v69, v42, v43
	v_cvt_pk_fp8_f32 v78, v40, v41
	v_mul_f32_e32 v80, v41, v41
	v_fmac_f32_e32 v80, v40, v40
	v_fmac_f32_e32 v80, v42, v42
	v_cvt_pk_fp8_f32 v78, v42, v43 op_sel:[0,0,1]
	v_fmac_f32_e32 v80, v43, v43
	v_add_f32_e32 v13, v13, v80
	s_waitcnt vmcnt(42)
; __device__ __forceinline__ unsigned cvt_pk_bf16(float lo, float hi) { unsigned r; asm("v_cvt_pk_bf16_f32 %0, %1, %2" : "=v"(r) : "v"(lo), "v"(hi)); return r; }
; __device__ __forceinline__ float wave_sum(float s, int) { s += dppf<0x128>(s); s += dppf<0x124>(s); s += dppf<0x122>(s); s += dppf<0x121>(s); return psum32(psum16(s)); }
; __device__ __forceinline__ void p0_prep(const Params& p, unsigned char* lds, int bid, int nb) {
;     ...
;     for (int row = bid * 8 + wid; row < T; row += nb * 8) {
;       const f32x4* src = (const f32x4*)(p.x + (size_t)row * D); float s = 0.f;
; #pragma unroll
;       for (int j = 0; j < 8; ++j) { const f32x4 v = src[lane + 64 * j]; s += v[0] * v[0] + v[1] * v[1] + v[2] * v[2] + v[3] * v[3];
;         u32x2 o; o[0] = cvt_pk_bf16(v[0], v[1]); o[1] = cvt_pk_bf16(v[2], v[3]); *(u32x2*)(xb + (size_t)row * D + (lane + 64 * j) * 4) = o;
;         unsigned q8 = __builtin_amdgcn_cvt_pk_fp8_f32(v[0], v[1], 0, false); q8 = __builtin_amdgcn_cvt_pk_fp8_f32(v[2], v[3], q8, true); *(unsigned*)(xq + (size_t)row * D + (lane + 64 * j) * 4) = q8; }
;       s = wave_sum(s, lane); if (lane == 0) ss0[row] = s;
;     }
	v_cvt_pk_bf16_f32 v70, v44, v45
	v_cvt_pk_bf16_f32 v71, v46, v47
	v_cvt_pk_fp8_f32 v79, v44, v45
	v_mul_f32_e32 v80, v45, v45
	v_fmac_f32_e32 v80, v44, v44
	v_fmac_f32_e32 v80, v46, v46
	v_cvt_pk_fp8_f32 v79, v46, v47 op_sel:[0,0,1]
	v_fmac_f32_e32 v80, v47, v47
	v_add_f32_e32 v13, v13, v80
	global_load_dwordx4 v[14:17], v[82:83], off offset:-4096
	global_load_dwordx4 v[18:21], v[82:83], off offset:-3072
	global_load_dwordx4 v[24:27], v[82:83], off offset:-2048
	global_load_dwordx4 v[28:31], v[82:83], off offset:-1024
	global_load_dwordx4 v[32:35], v[82:83], off
	global_load_dwordx4 v[36:39], v[82:83], off offset:1024
	global_load_dwordx4 v[40:43], v[82:83], off offset:2048
	global_load_dwordx4 v[44:47], v[82:83], off offset:3072
	v_lshl_add_u64 v[82:83], v[82:83], 0, s[16:17]
	global_store_dwordx2 v[8:9], v[56:57], off offset:-2048
	global_store_dword v[6:7], v72, off offset:-1024
	global_store_dwordx2 v[8:9], v[58:59], off offset:-1536
	global_store_dword v[6:7], v73, off offset:-768
	global_store_dwordx2 v[8:9], v[60:61], off offset:-1024
	global_store_dword v[6:7], v74, off offset:-512
	global_store_dwordx2 v[8:9], v[62:63], off offset:-512
	global_store_dword v[6:7], v75, off offset:-256
	global_store_dwordx2 v[8:9], v[64:65], off
	global_store_dword v[6:7], v76, off
	global_store_dwordx2 v[8:9], v[66:67], off offset:512
	global_store_dword v[6:7], v77, off offset:256
	global_store_dwordx2 v[8:9], v[68:69], off offset:1024
	global_store_dword v[6:7], v78, off offset:512
	global_store_dwordx2 v[8:9], v[70:71], off offset:1536
	global_store_dword v[6:7], v79, off offset:768
	v_add_f32_dpp v13, v13, v13 row_ror:8 row_mask:0xf bank_mask:0xf bound_ctrl:1
	s_nop 1
	v_add_f32_dpp v13, v13, v13 row_ror:4 row_mask:0xf bank_mask:0xf bound_ctrl:1
	s_nop 1
	v_add_f32_dpp v13, v13, v13 row_ror:2 row_mask:0xf bank_mask:0xf bound_ctrl:1
	s_nop 1
	v_add_f32_dpp v3, v13, v13 row_ror:1 row_mask:0xf bank_mask:0xf bound_ctrl:1
	v_mov_b32_e32 v13, v3
	s_nop 1
	v_permlane16_swap_b32_e32 v3, v13
	v_add_f32_e32 v3, v3, v13
	v_mov_b32_e32 v13, v3
	s_nop 1
	v_permlane32_swap_b32_e32 v3, v13
	s_and_saveexec_b64 s[4:5], vcc
	v_add_f32_e32 v3, v3, v13
	global_store_dword v[4:5], v3, off
	s_or_b64 exec, exec, s[4:5]
	v_lshl_add_u64 v[4:5], v[4:5], 0, s[10:11]
	v_lshl_add_u64 v[6:7], v[6:7], 0, s[12:13]
	v_lshl_add_u64 v[8:9], v[8:9], 0, s[14:15]
	s_waitcnt vmcnt(49)
	v_cvt_pk_bf16_f32 v56, v84, v85
	v_cvt_pk_bf16_f32 v57, v86, v87
	v_cvt_pk_fp8_f32 v72, v84, v85
	v_mul_f32_e32 v13, v85, v85
	v_fmac_f32_e32 v13, v84, v84
	v_fmac_f32_e32 v13, v86, v86
	v_cvt_pk_fp8_f32 v72, v86, v87 op_sel:[0,0,1]
	v_fmac_f32_e32 v13, v87, v87
	s_waitcnt vmcnt(48)
	v_cvt_pk_bf16_f32 v58, v88, v89
	v_cvt_pk_bf16_f32 v59, v90, v91
	v_cvt_pk_fp8_f32 v73, v88, v89
	v_mul_f32_e32 v80, v89, v89
	v_fmac_f32_e32 v80, v88, v88
	v_fmac_f32_e32 v80, v90, v90
	v_cvt_pk_fp8_f32 v73, v90, v91 op_sel:[0,0,1]
	v_fmac_f32_e32 v80, v91, v91
	v_add_f32_e32 v13, v13, v80
	s_waitcnt vmcnt(47)
	v_cvt_pk_bf16_f32 v60, v92, v93
	v_cvt_pk_bf16_f32 v61, v94, v95
	v_cvt_pk_fp8_f32 v74, v92, v93
	v_mul_f32_e32 v80, v93, v93
	v_fmac_f32_e32 v80, v92, v92
	v_fmac_f32_e32 v80, v94, v94
	v_cvt_pk_fp8_f32 v74, v94, v95 op_sel:[0,0,1]
	v_fmac_f32_e32 v80, v95, v95
	v_add_f32_e32 v13, v13, v80
	s_waitcnt vmcnt(46)
	v_cvt_pk_bf16_f32 v62, v96, v97
	v_cvt_pk_bf16_f32 v63, v98, v99
	v_cvt_pk_fp8_f32 v75, v96, v97
	v_mul_f32_e32 v80, v97, v97
	v_fmac_f32_e32 v80, v96, v96
	v_fmac_f32_e32 v80, v98, v98
	v_cvt_pk_fp8_f32 v75, v98, v99 op_sel:[0,0,1]
	v_fmac_f32_e32 v80, v99, v99
	v_add_f32_e32 v13, v13, v80
	s_waitcnt vmcnt(45)
	v_cvt_pk_bf16_f32 v64, v100, v101
	v_cvt_pk_bf16_f32 v65, v102, v103
	v_cvt_pk_fp8_f32 v76, v100, v101
	v_mul_f32_e32 v80, v101, v101
	v_fmac_f32_e32 v80, v100, v100
	v_fmac_f32_e32 v80, v102, v102
	v_cvt_pk_fp8_f32 v76, v102, v103 op_sel:[0,0,1]
	v_fmac_f32_e32 v80, v103, v103
	v_add_f32_e32 v13, v13, v80
	s_waitcnt vmcnt(44)
	v_cvt_pk_bf16_f32 v66, v104, v105
	v_cvt_pk_bf16_f32 v67, v106, v107
	v_cvt_pk_fp8_f32 v77, v104, v105
	v_mul_f32_e32 v80, v105, v105
	v_fmac_f32_e32 v80, v104, v104
	v_fmac_f32_e32 v80, v106, v106
	v_cvt_pk_fp8_f32 v77, v106, v107 op_sel:[0,0,1]
	v_fmac_f32_e32 v80, v107, v107
	v_add_f32_e32 v13, v13, v80
	s_waitcnt vmcnt(43)
	v_cvt_pk_bf16_f32 v68, v108, v109
	v_cvt_pk_bf16_f32 v69, v110, v111
	v_cvt_pk_fp8_f32 v78, v108, v109
	v_mul_f32_e32 v80, v109, v109
	v_fmac_f32_e32 v80, v108, v108
	v_fmac_f32_e32 v80, v110, v110
	v_cvt_pk_fp8_f32 v78, v110, v111 op_sel:[0,0,1]
	v_fmac_f32_e32 v80, v111, v111
	v_add_f32_e32 v13, v13, v80
	s_waitcnt vmcnt(42)
; __device__ __forceinline__ unsigned cvt_pk_bf16(float lo, float hi) { unsigned r; asm("v_cvt_pk_bf16_f32 %0, %1, %2" : "=v"(r) : "v"(lo), "v"(hi)); return r; }
; __device__ __forceinline__ float wave_sum(float s, int) { s += dppf<0x128>(s); s += dppf<0x124>(s); s += dppf<0x122>(s); s += dppf<0x121>(s); return psum32(psum16(s)); }
; __device__ __forceinline__ void p0_prep(const Params& p, unsigned char* lds, int bid, int nb) {
;     ...
;     for (int row = bid * 8 + wid; row < T; row += nb * 8) {
;       const f32x4* src = (const f32x4*)(p.x + (size_t)row * D); float s = 0.f;
; #pragma unroll
;       for (int j = 0; j < 8; ++j) { const f32x4 v = src[lane + 64 * j]; s += v[0] * v[0] + v[1] * v[1] + v[2] * v[2] + v[3] * v[3];
;         u32x2 o; o[0] = cvt_pk_bf16(v[0], v[1]); o[1] = cvt_pk_bf16(v[2], v[3]); *(u32x2*)(xb + (size_t)row * D + (lane + 64 * j) * 4) = o;
;         unsigned q8 = __builtin_amdgcn_cvt_pk_fp8_f32(v[0], v[1], 0, false); q8 = __builtin_amdgcn_cvt_pk_fp8_f32(v[2], v[3], q8, true); *(unsigned*)(xq + (size_t)row * D + (lane + 64 * j) * 4) = q8; }
;       s = wave_sum(s, lane); if (lane == 0) ss0[row] = s;
;     }
	v_cvt_pk_bf16_f32 v70, v112, v113
	v_cvt_pk_bf16_f32 v71, v114, v115
	v_cvt_pk_fp8_f32 v79, v112, v113
	v_mul_f32_e32 v80, v113, v113
	v_fmac_f32_e32 v80, v112, v112
	v_fmac_f32_e32 v80, v114, v114
	v_cvt_pk_fp8_f32 v79, v114, v115 op_sel:[0,0,1]
	v_fmac_f32_e32 v80, v115, v115
	v_add_f32_e32 v13, v13, v80
	global_load_dwordx4 v[84:87], v[82:83], off offset:-4096
	global_load_dwordx4 v[88:91], v[82:83], off offset:-3072
	global_load_dwordx4 v[92:95], v[82:83], off offset:-2048
	global_load_dwordx4 v[96:99], v[82:83], off offset:-1024
	global_load_dwordx4 v[100:103], v[82:83], off
	global_load_dwordx4 v[104:107], v[82:83], off offset:1024
	global_load_dwordx4 v[108:111], v[82:83], off offset:2048
	global_load_dwordx4 v[112:115], v[82:83], off offset:3072
	v_lshl_add_u64 v[82:83], v[82:83], 0, s[16:17]
	global_store_dwordx2 v[8:9], v[56:57], off offset:-2048
	global_store_dword v[6:7], v72, off offset:-1024
	global_store_dwordx2 v[8:9], v[58:59], off offset:-1536
	global_store_dword v[6:7], v73, off offset:-768
	global_store_dwordx2 v[8:9], v[60:61], off offset:-1024
	global_store_dword v[6:7], v74, off offset:-512
	global_store_dwordx2 v[8:9], v[62:63], off offset:-512
	global_store_dword v[6:7], v75, off offset:-256
	global_store_dwordx2 v[8:9], v[64:65], off
	global_store_dword v[6:7], v76, off
	global_store_dwordx2 v[8:9], v[66:67], off offset:512
	global_store_dword v[6:7], v77, off offset:256
	global_store_dwordx2 v[8:9], v[68:69], off offset:1024
	global_store_dword v[6:7], v78, off offset:512
	global_store_dwordx2 v[8:9], v[70:71], off offset:1536
	global_store_dword v[6:7], v79, off offset:768
	v_add_f32_dpp v13, v13, v13 row_ror:8 row_mask:0xf bank_mask:0xf bound_ctrl:1
	s_nop 1
	v_add_f32_dpp v13, v13, v13 row_ror:4 row_mask:0xf bank_mask:0xf bound_ctrl:1
	s_nop 1
	v_add_f32_dpp v13, v13, v13 row_ror:2 row_mask:0xf bank_mask:0xf bound_ctrl:1
	s_nop 1
	v_add_f32_dpp v3, v13, v13 row_ror:1 row_mask:0xf bank_mask:0xf bound_ctrl:1
	v_mov_b32_e32 v13, v3
	s_nop 1
	v_permlane16_swap_b32_e32 v3, v13
	v_add_f32_e32 v3, v3, v13
	v_mov_b32_e32 v13, v3
	s_nop 1
	v_permlane32_swap_b32_e32 v3, v13
	s_and_saveexec_b64 s[4:5], vcc
	v_add_f32_e32 v3, v3, v13
	global_store_dword v[4:5], v3, off
	s_or_b64 exec, exec, s[4:5]
	v_lshl_add_u64 v[4:5], v[4:5], 0, s[10:11]
	v_lshl_add_u64 v[6:7], v[6:7], 0, s[12:13]
	v_lshl_add_u64 v[8:9], v[8:9], 0, s[14:15]
	s_waitcnt vmcnt(49)
	v_cvt_pk_bf16_f32 v56, v14, v15
	v_cvt_pk_bf16_f32 v57, v16, v17
	v_cvt_pk_fp8_f32 v72, v14, v15
	v_mul_f32_e32 v13, v15, v15
	v_fmac_f32_e32 v13, v14, v14
	v_fmac_f32_e32 v13, v16, v16
	v_cvt_pk_fp8_f32 v72, v16, v17 op_sel:[0,0,1]
	v_fmac_f32_e32 v13, v17, v17
	s_waitcnt vmcnt(48)
	v_cvt_pk_bf16_f32 v58, v18, v19
	v_cvt_pk_bf16_f32 v59, v20, v21
	v_cvt_pk_fp8_f32 v73, v18, v19
	v_mul_f32_e32 v80, v19, v19
	v_fmac_f32_e32 v80, v18, v18
	v_fmac_f32_e32 v80, v20, v20
	v_cvt_pk_fp8_f32 v73, v20, v21 op_sel:[0,0,1]
	v_fmac_f32_e32 v80, v21, v21
	v_add_f32_e32 v13, v13, v80
	s_waitcnt vmcnt(47)
	v_cvt_pk_bf16_f32 v60, v24, v25
	v_cvt_pk_bf16_f32 v61, v26, v27
	v_cvt_pk_fp8_f32 v74, v24, v25
	v_mul_f32_e32 v80, v25, v25
	v_fmac_f32_e32 v80, v24, v24
	v_fmac_f32_e32 v80, v26, v26
	v_cvt_pk_fp8_f32 v74, v26, v27 op_sel:[0,0,1]
	v_fmac_f32_e32 v80, v27, v27
	v_add_f32_e32 v13, v13, v80
	s_waitcnt vmcnt(46)
	v_cvt_pk_bf16_f32 v62, v28, v29
	v_cvt_pk_bf16_f32 v63, v30, v31
	v_cvt_pk_fp8_f32 v75, v28, v29
	v_mul_f32_e32 v80, v29, v29
	v_fmac_f32_e32 v80, v28, v28
	v_fmac_f32_e32 v80, v30, v30
	v_cvt_pk_fp8_f32 v75, v30, v31 op_sel:[0,0,1]
	v_fmac_f32_e32 v80, v31, v31
	v_add_f32_e32 v13, v13, v80
	s_waitcnt vmcnt(45)
	v_cvt_pk_bf16_f32 v64, v32, v33
	v_cvt_pk_bf16_f32 v65, v34, v35
	v_cvt_pk_fp8_f32 v76, v32, v33
	v_mul_f32_e32 v80, v33, v33
	v_fmac_f32_e32 v80, v32, v32
	v_fmac_f32_e32 v80, v34, v34
	v_cvt_pk_fp8_f32 v76, v34, v35 op_sel:[0,0,1]
	v_fmac_f32_e32 v80, v35, v35
	v_add_f32_e32 v13, v13, v80
	s_waitcnt vmcnt(44)
	v_cvt_pk_bf16_f32 v66, v36, v37
	v_cvt_pk_bf16_f32 v67, v38, v39
	v_cvt_pk_fp8_f32 v77, v36, v37
	v_mul_f32_e32 v80, v37, v37
	v_fmac_f32_e32 v80, v36, v36
	v_fmac_f32_e32 v80, v38, v38
	v_cvt_pk_fp8_f32 v77, v38, v39 op_sel:[0,0,1]
	v_fmac_f32_e32 v80, v39, v39
	v_add_f32_e32 v13, v13, v80
	s_waitcnt vmcnt(43)
	v_cvt_pk_bf16_f32 v68, v40, v41
	v_cvt_pk_bf16_f32 v69, v42, v43
	v_cvt_pk_fp8_f32 v78, v40, v41
	v_mul_f32_e32 v80, v41, v41
	v_fmac_f32_e32 v80, v40, v40
	v_fmac_f32_e32 v80, v42, v42
	v_cvt_pk_fp8_f32 v78, v42, v43 op_sel:[0,0,1]
	v_fmac_f32_e32 v80, v43, v43
	v_add_f32_e32 v13, v13, v80
	s_waitcnt vmcnt(42)
; __device__ __forceinline__ unsigned cvt_pk_bf16(float lo, float hi) { unsigned r; asm("v_cvt_pk_bf16_f32 %0, %1, %2" : "=v"(r) : "v"(lo), "v"(hi)); return r; }
; __device__ __forceinline__ float wave_sum(float s, int) { s += dppf<0x128>(s); s += dppf<0x124>(s); s += dppf<0x122>(s); s += dppf<0x121>(s); return psum32(psum16(s)); }
; __device__ __forceinline__ void p0_prep(const Params& p, unsigned char* lds, int bid, int nb) {
;     ...
;     for (int row = bid * 8 + wid; row < T; row += nb * 8) {
;       const f32x4* src = (const f32x4*)(p.x + (size_t)row * D); float s = 0.f;
; #pragma unroll
;       for (int j = 0; j < 8; ++j) { const f32x4 v = src[lane + 64 * j]; s += v[0] * v[0] + v[1] * v[1] + v[2] * v[2] + v[3] * v[3];
;         u32x2 o; o[0] = cvt_pk_bf16(v[0], v[1]); o[1] = cvt_pk_bf16(v[2], v[3]); *(u32x2*)(xb + (size_t)row * D + (lane + 64 * j) * 4) = o;
;         unsigned q8 = __builtin_amdgcn_cvt_pk_fp8_f32(v[0], v[1], 0, false); q8 = __builtin_amdgcn_cvt_pk_fp8_f32(v[2], v[3], q8, true); *(unsigned*)(xq + (size_t)row * D + (lane + 64 * j) * 4) = q8; }
;       s = wave_sum(s, lane); if (lane == 0) ss0[row] = s;
;     }
	v_cvt_pk_bf16_f32 v70, v44, v45
	v_cvt_pk_bf16_f32 v71, v46, v47
	v_cvt_pk_fp8_f32 v79, v44, v45
	v_mul_f32_e32 v80, v45, v45
	v_fmac_f32_e32 v80, v44, v44
	v_fmac_f32_e32 v80, v46, v46
	v_cvt_pk_fp8_f32 v79, v46, v47 op_sel:[0,0,1]
	v_fmac_f32_e32 v80, v47, v47
	v_add_f32_e32 v13, v13, v80
	global_load_dwordx4 v[14:17], v[82:83], off offset:-4096
	global_load_dwordx4 v[18:21], v[82:83], off offset:-3072
	global_load_dwordx4 v[24:27], v[82:83], off offset:-2048
	global_load_dwordx4 v[28:31], v[82:83], off offset:-1024
	global_load_dwordx4 v[32:35], v[82:83], off
	global_load_dwordx4 v[36:39], v[82:83], off offset:1024
	global_load_dwordx4 v[40:43], v[82:83], off offset:2048
	global_load_dwordx4 v[44:47], v[82:83], off offset:3072
	v_lshl_add_u64 v[82:83], v[82:83], 0, s[16:17]
	global_store_dwordx2 v[8:9], v[56:57], off offset:-2048
	global_store_dword v[6:7], v72, off offset:-1024
	global_store_dwordx2 v[8:9], v[58:59], off offset:-1536
	global_store_dword v[6:7], v73, off offset:-768
	global_store_dwordx2 v[8:9], v[60:61], off offset:-1024
	global_store_dword v[6:7], v74, off offset:-512
	global_store_dwordx2 v[8:9], v[62:63], off offset:-512
	global_store_dword v[6:7], v75, off offset:-256
	global_store_dwordx2 v[8:9], v[64:65], off
	global_store_dword v[6:7], v76, off
	global_store_dwordx2 v[8:9], v[66:67], off offset:512
	global_store_dword v[6:7], v77, off offset:256
	global_store_dwordx2 v[8:9], v[68:69], off offset:1024
	global_store_dword v[6:7], v78, off offset:512
	global_store_dwordx2 v[8:9], v[70:71], off offset:1536
	global_store_dword v[6:7], v79, off offset:768
	v_add_f32_dpp v13, v13, v13 row_ror:8 row_mask:0xf bank_mask:0xf bound_ctrl:1
	s_nop 1
	v_add_f32_dpp v13, v13, v13 row_ror:4 row_mask:0xf bank_mask:0xf bound_ctrl:1
	s_nop 1
	v_add_f32_dpp v13, v13, v13 row_ror:2 row_mask:0xf bank_mask:0xf bound_ctrl:1
	s_nop 1
	v_add_f32_dpp v3, v13, v13 row_ror:1 row_mask:0xf bank_mask:0xf bound_ctrl:1
	v_mov_b32_e32 v13, v3
	s_nop 1
	v_permlane16_swap_b32_e32 v3, v13
	v_add_f32_e32 v3, v3, v13
	v_mov_b32_e32 v13, v3
	s_nop 1
	v_permlane32_swap_b32_e32 v3, v13
	s_and_saveexec_b64 s[4:5], vcc
	v_add_f32_e32 v3, v3, v13
	global_store_dword v[4:5], v3, off
	s_or_b64 exec, exec, s[4:5]
	v_lshl_add_u64 v[4:5], v[4:5], 0, s[10:11]
	v_lshl_add_u64 v[6:7], v[6:7], 0, s[12:13]
	v_lshl_add_u64 v[8:9], v[8:9], 0, s[14:15]
	s_waitcnt vmcnt(49)
	v_cvt_pk_bf16_f32 v56, v84, v85
	v_cvt_pk_bf16_f32 v57, v86, v87
	v_cvt_pk_fp8_f32 v72, v84, v85
	v_mul_f32_e32 v13, v85, v85
	v_fmac_f32_e32 v13, v84, v84
	v_fmac_f32_e32 v13, v86, v86
	v_cvt_pk_fp8_f32 v72, v86, v87 op_sel:[0,0,1]
	v_fmac_f32_e32 v13, v87, v87
	s_waitcnt vmcnt(48)
	v_cvt_pk_bf16_f32 v58, v88, v89
	v_cvt_pk_bf16_f32 v59, v90, v91
	v_cvt_pk_fp8_f32 v73, v88, v89
	v_mul_f32_e32 v80, v89, v89
	v_fmac_f32_e32 v80, v88, v88
	v_fmac_f32_e32 v80, v90, v90
	v_cvt_pk_fp8_f32 v73, v90, v91 op_sel:[0,0,1]
	v_fmac_f32_e32 v80, v91, v91
	v_add_f32_e32 v13, v13, v80
	s_waitcnt vmcnt(47)
	v_cvt_pk_bf16_f32 v60, v92, v93
	v_cvt_pk_bf16_f32 v61, v94, v95
	v_cvt_pk_fp8_f32 v74, v92, v93
	v_mul_f32_e32 v80, v93, v93
	v_fmac_f32_e32 v80, v92, v92
	v_fmac_f32_e32 v80, v94, v94
	v_cvt_pk_fp8_f32 v74, v94, v95 op_sel:[0,0,1]
	v_fmac_f32_e32 v80, v95, v95
	v_add_f32_e32 v13, v13, v80
	s_waitcnt vmcnt(46)
	v_cvt_pk_bf16_f32 v62, v96, v97
	v_cvt_pk_bf16_f32 v63, v98, v99
	v_cvt_pk_fp8_f32 v75, v96, v97
	v_mul_f32_e32 v80, v97, v97
	v_fmac_f32_e32 v80, v96, v96
	v_fmac_f32_e32 v80, v98, v98
	v_cvt_pk_fp8_f32 v75, v98, v99 op_sel:[0,0,1]
	v_fmac_f32_e32 v80, v99, v99
	v_add_f32_e32 v13, v13, v80
	s_waitcnt vmcnt(45)
	v_cvt_pk_bf16_f32 v64, v100, v101
	v_cvt_pk_bf16_f32 v65, v102, v103
	v_cvt_pk_fp8_f32 v76, v100, v101
	v_mul_f32_e32 v80, v101, v101
	v_fmac_f32_e32 v80, v100, v100
	v_fmac_f32_e32 v80, v102, v102
	v_cvt_pk_fp8_f32 v76, v102, v103 op_sel:[0,0,1]
	v_fmac_f32_e32 v80, v103, v103
	v_add_f32_e32 v13, v13, v80
	s_waitcnt vmcnt(44)
	v_cvt_pk_bf16_f32 v66, v104, v105
	v_cvt_pk_bf16_f32 v67, v106, v107
	v_cvt_pk_fp8_f32 v77, v104, v105
	v_mul_f32_e32 v80, v105, v105
	v_fmac_f32_e32 v80, v104, v104
	v_fmac_f32_e32 v80, v106, v106
	v_cvt_pk_fp8_f32 v77, v106, v107 op_sel:[0,0,1]
	v_fmac_f32_e32 v80, v107, v107
	v_add_f32_e32 v13, v13, v80
	s_waitcnt vmcnt(43)
	v_cvt_pk_bf16_f32 v68, v108, v109
	v_cvt_pk_bf16_f32 v69, v110, v111
	v_cvt_pk_fp8_f32 v78, v108, v109
	v_mul_f32_e32 v80, v109, v109
	v_fmac_f32_e32 v80, v108, v108
	v_fmac_f32_e32 v80, v110, v110
	v_cvt_pk_fp8_f32 v78, v110, v111 op_sel:[0,0,1]
	v_fmac_f32_e32 v80, v111, v111
	v_add_f32_e32 v13, v13, v80
	s_waitcnt vmcnt(42)
; __device__ __forceinline__ unsigned cvt_pk_bf16(float lo, float hi) { unsigned r; asm("v_cvt_pk_bf16_f32 %0, %1, %2" : "=v"(r) : "v"(lo), "v"(hi)); return r; }
; __device__ __forceinline__ float wave_sum(float s, int) { s += dppf<0x128>(s); s += dppf<0x124>(s); s += dppf<0x122>(s); s += dppf<0x121>(s); return psum32(psum16(s)); }
; __device__ __forceinline__ void p0_prep(const Params& p, unsigned char* lds, int bid, int nb) {
;     ...
;     for (int row = bid * 8 + wid; row < T; row += nb * 8) {
;       const f32x4* src = (const f32x4*)(p.x + (size_t)row * D); float s = 0.f;
; #pragma unroll
;       for (int j = 0; j < 8; ++j) { const f32x4 v = src[lane + 64 * j]; s += v[0] * v[0] + v[1] * v[1] + v[2] * v[2] + v[3] * v[3];
;         u32x2 o; o[0] = cvt_pk_bf16(v[0], v[1]); o[1] = cvt_pk_bf16(v[2], v[3]); *(u32x2*)(xb + (size_t)row * D + (lane + 64 * j) * 4) = o;
;         unsigned q8 = __builtin_amdgcn_cvt_pk_fp8_f32(v[0], v[1], 0, false); q8 = __builtin_amdgcn_cvt_pk_fp8_f32(v[2], v[3], q8, true); *(unsigned*)(xq + (size_t)row * D + (lane + 64 * j) * 4) = q8; }
;       s = wave_sum(s, lane); if (lane == 0) ss0[row] = s;
;     }
	v_cvt_pk_bf16_f32 v70, v112, v113
	v_cvt_pk_bf16_f32 v71, v114, v115
	v_cvt_pk_fp8_f32 v79, v112, v113
	v_mul_f32_e32 v80, v113, v113
	v_fmac_f32_e32 v80, v112, v112
	v_fmac_f32_e32 v80, v114, v114
	v_cvt_pk_fp8_f32 v79, v114, v115 op_sel:[0,0,1]
	v_fmac_f32_e32 v80, v115, v115
	v_add_f32_e32 v13, v13, v80
	global_load_dwordx4 v[84:87], v[82:83], off offset:-4096
	global_load_dwordx4 v[88:91], v[82:83], off offset:-3072
	global_load_dwordx4 v[92:95], v[82:83], off offset:-2048
	global_load_dwordx4 v[96:99], v[82:83], off offset:-1024
	global_load_dwordx4 v[100:103], v[82:83], off
	global_load_dwordx4 v[104:107], v[82:83], off offset:1024
	global_load_dwordx4 v[108:111], v[82:83], off offset:2048
	global_load_dwordx4 v[112:115], v[82:83], off offset:3072
	v_lshl_add_u64 v[82:83], v[82:83], 0, s[16:17]
	global_store_dwordx2 v[8:9], v[56:57], off offset:-2048
	global_store_dword v[6:7], v72, off offset:-1024
	global_store_dwordx2 v[8:9], v[58:59], off offset:-1536
	global_store_dword v[6:7], v73, off offset:-768
	global_store_dwordx2 v[8:9], v[60:61], off offset:-1024
	global_store_dword v[6:7], v74, off offset:-512
	global_store_dwordx2 v[8:9], v[62:63], off offset:-512
	global_store_dword v[6:7], v75, off offset:-256
	global_store_dwordx2 v[8:9], v[64:65], off
	global_store_dword v[6:7], v76, off
	global_store_dwordx2 v[8:9], v[66:67], off offset:512
	global_store_dword v[6:7], v77, off offset:256
	global_store_dwordx2 v[8:9], v[68:69], off offset:1024
	global_store_dword v[6:7], v78, off offset:512
	global_store_dwordx2 v[8:9], v[70:71], off offset:1536
	global_store_dword v[6:7], v79, off offset:768
	v_add_f32_dpp v13, v13, v13 row_ror:8 row_mask:0xf bank_mask:0xf bound_ctrl:1
	s_nop 1
	v_add_f32_dpp v13, v13, v13 row_ror:4 row_mask:0xf bank_mask:0xf bound_ctrl:1
	s_nop 1
	v_add_f32_dpp v13, v13, v13 row_ror:2 row_mask:0xf bank_mask:0xf bound_ctrl:1
	s_nop 1
	v_add_f32_dpp v3, v13, v13 row_ror:1 row_mask:0xf bank_mask:0xf bound_ctrl:1
	v_mov_b32_e32 v13, v3
	s_nop 1
	v_permlane16_swap_b32_e32 v3, v13
	v_add_f32_e32 v3, v3, v13
	v_mov_b32_e32 v13, v3
	s_nop 1
	v_permlane32_swap_b32_e32 v3, v13
	s_and_saveexec_b64 s[4:5], vcc
	v_add_f32_e32 v3, v3, v13
	global_store_dword v[4:5], v3, off
	s_or_b64 exec, exec, s[4:5]
	v_lshl_add_u64 v[4:5], v[4:5], 0, s[10:11]
	v_lshl_add_u64 v[6:7], v[6:7], 0, s[12:13]
	v_lshl_add_u64 v[8:9], v[8:9], 0, s[14:15]
	s_waitcnt vmcnt(49)
	v_cvt_pk_bf16_f32 v56, v14, v15
	v_cvt_pk_bf16_f32 v57, v16, v17
	v_cvt_pk_fp8_f32 v72, v14, v15
	v_mul_f32_e32 v13, v15, v15
	v_fmac_f32_e32 v13, v14, v14
	v_fmac_f32_e32 v13, v16, v16
	v_cvt_pk_fp8_f32 v72, v16, v17 op_sel:[0,0,1]
	v_fmac_f32_e32 v13, v17, v17
	s_waitcnt vmcnt(48)
	v_cvt_pk_bf16_f32 v58, v18, v19
	v_cvt_pk_bf16_f32 v59, v20, v21
	v_cvt_pk_fp8_f32 v73, v18, v19
	v_mul_f32_e32 v80, v19, v19
	v_fmac_f32_e32 v80, v18, v18
	v_fmac_f32_e32 v80, v20, v20
	v_cvt_pk_fp8_f32 v73, v20, v21 op_sel:[0,0,1]
	v_fmac_f32_e32 v80, v21, v21
	v_add_f32_e32 v13, v13, v80
	s_waitcnt vmcnt(47)
	v_cvt_pk_bf16_f32 v60, v24, v25
	v_cvt_pk_bf16_f32 v61, v26, v27
	v_cvt_pk_fp8_f32 v74, v24, v25
	v_mul_f32_e32 v80, v25, v25
	v_fmac_f32_e32 v80, v24, v24
	v_fmac_f32_e32 v80, v26, v26
	v_cvt_pk_fp8_f32 v74, v26, v27 op_sel:[0,0,1]
	v_fmac_f32_e32 v80, v27, v27
	v_add_f32_e32 v13, v13, v80
	s_waitcnt vmcnt(46)
	v_cvt_pk_bf16_f32 v62, v28, v29
	v_cvt_pk_bf16_f32 v63, v30, v31
	v_cvt_pk_fp8_f32 v75, v28, v29
	v_mul_f32_e32 v80, v29, v29
	v_fmac_f32_e32 v80, v28, v28
	v_fmac_f32_e32 v80, v30, v30
	v_cvt_pk_fp8_f32 v75, v30, v31 op_sel:[0,0,1]
	v_fmac_f32_e32 v80, v31, v31
	v_add_f32_e32 v13, v13, v80
	s_waitcnt vmcnt(45)
	v_cvt_pk_bf16_f32 v64, v32, v33
	v_cvt_pk_bf16_f32 v65, v34, v35
	v_cvt_pk_fp8_f32 v76, v32, v33
	v_mul_f32_e32 v80, v33, v33
	v_fmac_f32_e32 v80, v32, v32
	v_fmac_f32_e32 v80, v34, v34
	v_cvt_pk_fp8_f32 v76, v34, v35 op_sel:[0,0,1]
	v_fmac_f32_e32 v80, v35, v35
	v_add_f32_e32 v13, v13, v80
	s_waitcnt vmcnt(44)
	v_cvt_pk_bf16_f32 v66, v36, v37
	v_cvt_pk_bf16_f32 v67, v38, v39
	v_cvt_pk_fp8_f32 v77, v36, v37
	v_mul_f32_e32 v80, v37, v37
	v_fmac_f32_e32 v80, v36, v36
	v_fmac_f32_e32 v80, v38, v38
	v_cvt_pk_fp8_f32 v77, v38, v39 op_sel:[0,0,1]
	v_fmac_f32_e32 v80, v39, v39
	v_add_f32_e32 v13, v13, v80
	s_waitcnt vmcnt(43)
	v_cvt_pk_bf16_f32 v68, v40, v41
	v_cvt_pk_bf16_f32 v69, v42, v43
	v_cvt_pk_fp8_f32 v78, v40, v41
	v_mul_f32_e32 v80, v41, v41
	v_fmac_f32_e32 v80, v40, v40
	v_fmac_f32_e32 v80, v42, v42
	v_cvt_pk_fp8_f32 v78, v42, v43 op_sel:[0,0,1]
	v_fmac_f32_e32 v80, v43, v43
	v_add_f32_e32 v13, v13, v80
	s_waitcnt vmcnt(42)
; __device__ __forceinline__ unsigned cvt_pk_bf16(float lo, float hi) { unsigned r; asm("v_cvt_pk_bf16_f32 %0, %1, %2" : "=v"(r) : "v"(lo), "v"(hi)); return r; }
; __device__ __forceinline__ float wave_sum(float s, int) { s += dppf<0x128>(s); s += dppf<0x124>(s); s += dppf<0x122>(s); s += dppf<0x121>(s); return psum32(psum16(s)); }
; __device__ __forceinline__ void p0_prep(const Params& p, unsigned char* lds, int bid, int nb) {
;     ...
;     for (int row = bid * 8 + wid; row < T; row += nb * 8) {
;       const f32x4* src = (const f32x4*)(p.x + (size_t)row * D); float s = 0.f;
; #pragma unroll
;       for (int j = 0; j < 8; ++j) { const f32x4 v = src[lane + 64 * j]; s += v[0] * v[0] + v[1] * v[1] + v[2] * v[2] + v[3] * v[3];
;         u32x2 o; o[0] = cvt_pk_bf16(v[0], v[1]); o[1] = cvt_pk_bf16(v[2], v[3]); *(u32x2*)(xb + (size_t)row * D + (lane + 64 * j) * 4) = o;
;         unsigned q8 = __builtin_amdgcn_cvt_pk_fp8_f32(v[0], v[1], 0, false); q8 = __builtin_amdgcn_cvt_pk_fp8_f32(v[2], v[3], q8, true); *(unsigned*)(xq + (size_t)row * D + (lane + 64 * j) * 4) = q8; }
;       s = wave_sum(s, lane); if (lane == 0) ss0[row] = s;
;     }
	v_cvt_pk_bf16_f32 v70, v44, v45
	v_cvt_pk_bf16_f32 v71, v46, v47
	v_cvt_pk_fp8_f32 v79, v44, v45
	v_mul_f32_e32 v80, v45, v45
	v_fmac_f32_e32 v80, v44, v44
	v_fmac_f32_e32 v80, v46, v46
	v_cvt_pk_fp8_f32 v79, v46, v47 op_sel:[0,0,1]
	v_fmac_f32_e32 v80, v47, v47
	v_add_f32_e32 v13, v13, v80
	global_load_dwordx4 v[14:17], v[82:83], off offset:-4096
	global_load_dwordx4 v[18:21], v[82:83], off offset:-3072
	global_load_dwordx4 v[24:27], v[82:83], off offset:-2048
	global_load_dwordx4 v[28:31], v[82:83], off offset:-1024
	global_load_dwordx4 v[32:35], v[82:83], off
	global_load_dwordx4 v[36:39], v[82:83], off offset:1024
	global_load_dwordx4 v[40:43], v[82:83], off offset:2048
	global_load_dwordx4 v[44:47], v[82:83], off offset:3072
	v_lshl_add_u64 v[82:83], v[82:83], 0, s[16:17]
	global_store_dwordx2 v[8:9], v[56:57], off offset:-2048
	global_store_dword v[6:7], v72, off offset:-1024
	global_store_dwordx2 v[8:9], v[58:59], off offset:-1536
	global_store_dword v[6:7], v73, off offset:-768
	global_store_dwordx2 v[8:9], v[60:61], off offset:-1024
	global_store_dword v[6:7], v74, off offset:-512
	global_store_dwordx2 v[8:9], v[62:63], off offset:-512
	global_store_dword v[6:7], v75, off offset:-256
	global_store_dwordx2 v[8:9], v[64:65], off
	global_store_dword v[6:7], v76, off
	global_store_dwordx2 v[8:9], v[66:67], off offset:512
	global_store_dword v[6:7], v77, off offset:256
	global_store_dwordx2 v[8:9], v[68:69], off offset:1024
	global_store_dword v[6:7], v78, off offset:512
	global_store_dwordx2 v[8:9], v[70:71], off offset:1536
	global_store_dword v[6:7], v79, off offset:768
	v_add_f32_dpp v13, v13, v13 row_ror:8 row_mask:0xf bank_mask:0xf bound_ctrl:1
	s_nop 1
	v_add_f32_dpp v13, v13, v13 row_ror:4 row_mask:0xf bank_mask:0xf bound_ctrl:1
	s_nop 1
	v_add_f32_dpp v13, v13, v13 row_ror:2 row_mask:0xf bank_mask:0xf bound_ctrl:1
	s_nop 1
	v_add_f32_dpp v3, v13, v13 row_ror:1 row_mask:0xf bank_mask:0xf bound_ctrl:1
	v_mov_b32_e32 v13, v3
	s_nop 1
	v_permlane16_swap_b32_e32 v3, v13
	v_add_f32_e32 v3, v3, v13
	v_mov_b32_e32 v13, v3
	s_nop 1
	v_permlane32_swap_b32_e32 v3, v13
	s_and_saveexec_b64 s[4:5], vcc
	v_add_f32_e32 v3, v3, v13
	global_store_dword v[4:5], v3, off
	s_or_b64 exec, exec, s[4:5]
	v_lshl_add_u64 v[4:5], v[4:5], 0, s[10:11]
	v_lshl_add_u64 v[6:7], v[6:7], 0, s[12:13]
	v_lshl_add_u64 v[8:9], v[8:9], 0, s[14:15]
	s_waitcnt vmcnt(49)
	v_cvt_pk_bf16_f32 v56, v84, v85
	v_cvt_pk_bf16_f32 v57, v86, v87
	v_cvt_pk_fp8_f32 v72, v84, v85
	v_mul_f32_e32 v13, v85, v85
	v_fmac_f32_e32 v13, v84, v84
	v_fmac_f32_e32 v13, v86, v86
	v_cvt_pk_fp8_f32 v72, v86, v87 op_sel:[0,0,1]
	v_fmac_f32_e32 v13, v87, v87
	s_waitcnt vmcnt(48)
	v_cvt_pk_bf16_f32 v58, v88, v89
	v_cvt_pk_bf16_f32 v59, v90, v91
	v_cvt_pk_fp8_f32 v73, v88, v89
	v_mul_f32_e32 v80, v89, v89
	v_fmac_f32_e32 v80, v88, v88
	v_fmac_f32_e32 v80, v90, v90
	v_cvt_pk_fp8_f32 v73, v90, v91 op_sel:[0,0,1]
	v_fmac_f32_e32 v80, v91, v91
	v_add_f32_e32 v13, v13, v80
	s_waitcnt vmcnt(47)
	v_cvt_pk_bf16_f32 v60, v92, v93
	v_cvt_pk_bf16_f32 v61, v94, v95
	v_cvt_pk_fp8_f32 v74, v92, v93
	v_mul_f32_e32 v80, v93, v93
	v_fmac_f32_e32 v80, v92, v92
	v_fmac_f32_e32 v80, v94, v94
	v_cvt_pk_fp8_f32 v74, v94, v95 op_sel:[0,0,1]
	v_fmac_f32_e32 v80, v95, v95
	v_add_f32_e32 v13, v13, v80
	s_waitcnt vmcnt(46)
	v_cvt_pk_bf16_f32 v62, v96, v97
	v_cvt_pk_bf16_f32 v63, v98, v99
	v_cvt_pk_fp8_f32 v75, v96, v97
	v_mul_f32_e32 v80, v97, v97
	v_fmac_f32_e32 v80, v96, v96
	v_fmac_f32_e32 v80, v98, v98
	v_cvt_pk_fp8_f32 v75, v98, v99 op_sel:[0,0,1]
	v_fmac_f32_e32 v80, v99, v99
	v_add_f32_e32 v13, v13, v80
	s_waitcnt vmcnt(45)
	v_cvt_pk_bf16_f32 v64, v100, v101
	v_cvt_pk_bf16_f32 v65, v102, v103
	v_cvt_pk_fp8_f32 v76, v100, v101
	v_mul_f32_e32 v80, v101, v101
	v_fmac_f32_e32 v80, v100, v100
	v_fmac_f32_e32 v80, v102, v102
	v_cvt_pk_fp8_f32 v76, v102, v103 op_sel:[0,0,1]
	v_fmac_f32_e32 v80, v103, v103
	v_add_f32_e32 v13, v13, v80
	s_waitcnt vmcnt(44)
	v_cvt_pk_bf16_f32 v66, v104, v105
	v_cvt_pk_bf16_f32 v67, v106, v107
	v_cvt_pk_fp8_f32 v77, v104, v105
	v_mul_f32_e32 v80, v105, v105
	v_fmac_f32_e32 v80, v104, v104
	v_fmac_f32_e32 v80, v106, v106
	v_cvt_pk_fp8_f32 v77, v106, v107 op_sel:[0,0,1]
	v_fmac_f32_e32 v80, v107, v107
	v_add_f32_e32 v13, v13, v80
	s_waitcnt vmcnt(43)
	v_cvt_pk_bf16_f32 v68, v108, v109
	v_cvt_pk_bf16_f32 v69, v110, v111
	v_cvt_pk_fp8_f32 v78, v108, v109
	v_mul_f32_e32 v80, v109, v109
	v_fmac_f32_e32 v80, v108, v108
	v_fmac_f32_e32 v80, v110, v110
	v_cvt_pk_fp8_f32 v78, v110, v111 op_sel:[0,0,1]
	v_fmac_f32_e32 v80, v111, v111
	v_add_f32_e32 v13, v13, v80
	s_waitcnt vmcnt(42)
; __device__ __forceinline__ unsigned cvt_pk_bf16(float lo, float hi) { unsigned r; asm("v_cvt_pk_bf16_f32 %0, %1, %2" : "=v"(r) : "v"(lo), "v"(hi)); return r; }
; __device__ __forceinline__ float wave_sum(float s, int) { s += dppf<0x128>(s); s += dppf<0x124>(s); s += dppf<0x122>(s); s += dppf<0x121>(s); return psum32(psum16(s)); }
; __device__ __forceinline__ void p0_prep(const Params& p, unsigned char* lds, int bid, int nb) {
;     ...
;     for (int row = bid * 8 + wid; row < T; row += nb * 8) {
;       const f32x4* src = (const f32x4*)(p.x + (size_t)row * D); float s = 0.f;
; #pragma unroll
;       for (int j = 0; j < 8; ++j) { const f32x4 v = src[lane + 64 * j]; s += v[0] * v[0] + v[1] * v[1] + v[2] * v[2] + v[3] * v[3];
;         u32x2 o; o[0] = cvt_pk_bf16(v[0], v[1]); o[1] = cvt_pk_bf16(v[2], v[3]); *(u32x2*)(xb + (size_t)row * D + (lane + 64 * j) * 4) = o;
;         unsigned q8 = __builtin_amdgcn_cvt_pk_fp8_f32(v[0], v[1], 0, false); q8 = __builtin_amdgcn_cvt_pk_fp8_f32(v[2], v[3], q8, true); *(unsigned*)(xq + (size_t)row * D + (lane + 64 * j) * 4) = q8; }
;       s = wave_sum(s, lane); if (lane == 0) ss0[row] = s;
;     }
	v_cvt_pk_bf16_f32 v70, v112, v113
	v_cvt_pk_bf16_f32 v71, v114, v115
	v_cvt_pk_fp8_f32 v79, v112, v113
	v_mul_f32_e32 v80, v113, v113
	v_fmac_f32_e32 v80, v112, v112
	v_fmac_f32_e32 v80, v114, v114
	v_cvt_pk_fp8_f32 v79, v114, v115 op_sel:[0,0,1]
	v_fmac_f32_e32 v80, v115, v115
	v_add_f32_e32 v13, v13, v80
	global_load_dwordx4 v[84:87], v[82:83], off offset:-4096
	global_load_dwordx4 v[88:91], v[82:83], off offset:-3072
	global_load_dwordx4 v[92:95], v[82:83], off offset:-2048
	global_load_dwordx4 v[96:99], v[82:83], off offset:-1024
	global_load_dwordx4 v[100:103], v[82:83], off
	global_load_dwordx4 v[104:107], v[82:83], off offset:1024
	global_load_dwordx4 v[108:111], v[82:83], off offset:2048
	global_load_dwordx4 v[112:115], v[82:83], off offset:3072
	v_lshl_add_u64 v[82:83], v[82:83], 0, s[16:17]
	global_store_dwordx2 v[8:9], v[56:57], off offset:-2048
	global_store_dword v[6:7], v72, off offset:-1024
	global_store_dwordx2 v[8:9], v[58:59], off offset:-1536
	global_store_dword v[6:7], v73, off offset:-768
	global_store_dwordx2 v[8:9], v[60:61], off offset:-1024
	global_store_dword v[6:7], v74, off offset:-512
	global_store_dwordx2 v[8:9], v[62:63], off offset:-512
	global_store_dword v[6:7], v75, off offset:-256
	global_store_dwordx2 v[8:9], v[64:65], off
	global_store_dword v[6:7], v76, off
	global_store_dwordx2 v[8:9], v[66:67], off offset:512
	global_store_dword v[6:7], v77, off offset:256
	global_store_dwordx2 v[8:9], v[68:69], off offset:1024
	global_store_dword v[6:7], v78, off offset:512
	global_store_dwordx2 v[8:9], v[70:71], off offset:1536
	global_store_dword v[6:7], v79, off offset:768
	v_add_f32_dpp v13, v13, v13 row_ror:8 row_mask:0xf bank_mask:0xf bound_ctrl:1
	s_nop 1
	v_add_f32_dpp v13, v13, v13 row_ror:4 row_mask:0xf bank_mask:0xf bound_ctrl:1
	s_nop 1
	v_add_f32_dpp v13, v13, v13 row_ror:2 row_mask:0xf bank_mask:0xf bound_ctrl:1
	s_nop 1
	v_add_f32_dpp v3, v13, v13 row_ror:1 row_mask:0xf bank_mask:0xf bound_ctrl:1
	v_mov_b32_e32 v13, v3
	s_nop 1
	v_permlane16_swap_b32_e32 v3, v13
	v_add_f32_e32 v3, v3, v13
	v_mov_b32_e32 v13, v3
	s_nop 1
	v_permlane32_swap_b32_e32 v3, v13
	s_and_saveexec_b64 s[4:5], vcc
	v_add_f32_e32 v3, v3, v13
	global_store_dword v[4:5], v3, off
	s_or_b64 exec, exec, s[4:5]
	v_lshl_add_u64 v[4:5], v[4:5], 0, s[10:11]
	v_lshl_add_u64 v[6:7], v[6:7], 0, s[12:13]
	v_lshl_add_u64 v[8:9], v[8:9], 0, s[14:15]
	s_waitcnt vmcnt(49)
	v_cvt_pk_bf16_f32 v56, v14, v15
	v_cvt_pk_bf16_f32 v57, v16, v17
	v_cvt_pk_fp8_f32 v72, v14, v15
	v_mul_f32_e32 v13, v15, v15
	v_fmac_f32_e32 v13, v14, v14
	v_fmac_f32_e32 v13, v16, v16
	v_cvt_pk_fp8_f32 v72, v16, v17 op_sel:[0,0,1]
	v_fmac_f32_e32 v13, v17, v17
	s_waitcnt vmcnt(48)
	v_cvt_pk_bf16_f32 v58, v18, v19
	v_cvt_pk_bf16_f32 v59, v20, v21
	v_cvt_pk_fp8_f32 v73, v18, v19
	v_mul_f32_e32 v80, v19, v19
	v_fmac_f32_e32 v80, v18, v18
	v_fmac_f32_e32 v80, v20, v20
	v_cvt_pk_fp8_f32 v73, v20, v21 op_sel:[0,0,1]
	v_fmac_f32_e32 v80, v21, v21
	v_add_f32_e32 v13, v13, v80
	s_waitcnt vmcnt(47)
	v_cvt_pk_bf16_f32 v60, v24, v25
	v_cvt_pk_bf16_f32 v61, v26, v27
	v_cvt_pk_fp8_f32 v74, v24, v25
	v_mul_f32_e32 v80, v25, v25
	v_fmac_f32_e32 v80, v24, v24
	v_fmac_f32_e32 v80, v26, v26
	v_cvt_pk_fp8_f32 v74, v26, v27 op_sel:[0,0,1]
	v_fmac_f32_e32 v80, v27, v27
	v_add_f32_e32 v13, v13, v80
	s_waitcnt vmcnt(46)
	v_cvt_pk_bf16_f32 v62, v28, v29
	v_cvt_pk_bf16_f32 v63, v30, v31
	v_cvt_pk_fp8_f32 v75, v28, v29
	v_mul_f32_e32 v80, v29, v29
	v_fmac_f32_e32 v80, v28, v28
	v_fmac_f32_e32 v80, v30, v30
	v_cvt_pk_fp8_f32 v75, v30, v31 op_sel:[0,0,1]
	v_fmac_f32_e32 v80, v31, v31
	v_add_f32_e32 v13, v13, v80
	s_waitcnt vmcnt(45)
	v_cvt_pk_bf16_f32 v64, v32, v33
	v_cvt_pk_bf16_f32 v65, v34, v35
	v_cvt_pk_fp8_f32 v76, v32, v33
	v_mul_f32_e32 v80, v33, v33
	v_fmac_f32_e32 v80, v32, v32
	v_fmac_f32_e32 v80, v34, v34
	v_cvt_pk_fp8_f32 v76, v34, v35 op_sel:[0,0,1]
	v_fmac_f32_e32 v80, v35, v35
	v_add_f32_e32 v13, v13, v80
	s_waitcnt vmcnt(44)
	v_cvt_pk_bf16_f32 v66, v36, v37
	v_cvt_pk_bf16_f32 v67, v38, v39
	v_cvt_pk_fp8_f32 v77, v36, v37
	v_mul_f32_e32 v80, v37, v37
	v_fmac_f32_e32 v80, v36, v36
	v_fmac_f32_e32 v80, v38, v38
	v_cvt_pk_fp8_f32 v77, v38, v39 op_sel:[0,0,1]
	v_fmac_f32_e32 v80, v39, v39
	v_add_f32_e32 v13, v13, v80
	s_waitcnt vmcnt(43)
	v_cvt_pk_bf16_f32 v68, v40, v41
	v_cvt_pk_bf16_f32 v69, v42, v43
	v_cvt_pk_fp8_f32 v78, v40, v41
	v_mul_f32_e32 v80, v41, v41
	v_fmac_f32_e32 v80, v40, v40
	v_fmac_f32_e32 v80, v42, v42
	v_cvt_pk_fp8_f32 v78, v42, v43 op_sel:[0,0,1]
	v_fmac_f32_e32 v80, v43, v43
	v_add_f32_e32 v13, v13, v80
	s_waitcnt vmcnt(42)
; __device__ __forceinline__ unsigned cvt_pk_bf16(float lo, float hi) { unsigned r; asm("v_cvt_pk_bf16_f32 %0, %1, %2" : "=v"(r) : "v"(lo), "v"(hi)); return r; }
; __device__ __forceinline__ float wave_sum(float s, int) { s += dppf<0x128>(s); s += dppf<0x124>(s); s += dppf<0x122>(s); s += dppf<0x121>(s); return psum32(psum16(s)); }
; __device__ __forceinline__ void p0_prep(const Params& p, unsigned char* lds, int bid, int nb) {
;     ...
;     for (int row = bid * 8 + wid; row < T; row += nb * 8) {
;       const f32x4* src = (const f32x4*)(p.x + (size_t)row * D); float s = 0.f;
; #pragma unroll
;       for (int j = 0; j < 8; ++j) { const f32x4 v = src[lane + 64 * j]; s += v[0] * v[0] + v[1] * v[1] + v[2] * v[2] + v[3] * v[3];
;         u32x2 o; o[0] = cvt_pk_bf16(v[0], v[1]); o[1] = cvt_pk_bf16(v[2], v[3]); *(u32x2*)(xb + (size_t)row * D + (lane + 64 * j) * 4) = o;
;         unsigned q8 = __builtin_amdgcn_cvt_pk_fp8_f32(v[0], v[1], 0, false); q8 = __builtin_amdgcn_cvt_pk_fp8_f32(v[2], v[3], q8, true); *(unsigned*)(xq + (size_t)row * D + (lane + 64 * j) * 4) = q8; }
;       s = wave_sum(s, lane); if (lane == 0) ss0[row] = s;
;     }
	v_cvt_pk_bf16_f32 v70, v44, v45
	v_cvt_pk_bf16_f32 v71, v46, v47
	v_cvt_pk_fp8_f32 v79, v44, v45
	v_mul_f32_e32 v80, v45, v45
	v_fmac_f32_e32 v80, v44, v44
	v_fmac_f32_e32 v80, v46, v46
	v_cvt_pk_fp8_f32 v79, v46, v47 op_sel:[0,0,1]
	v_fmac_f32_e32 v80, v47, v47
	v_add_f32_e32 v13, v13, v80
	global_store_dwordx2 v[8:9], v[56:57], off offset:-2048
	global_store_dword v[6:7], v72, off offset:-1024
	global_store_dwordx2 v[8:9], v[58:59], off offset:-1536
	global_store_dword v[6:7], v73, off offset:-768
	global_store_dwordx2 v[8:9], v[60:61], off offset:-1024
	global_store_dword v[6:7], v74, off offset:-512
	global_store_dwordx2 v[8:9], v[62:63], off offset:-512
	global_store_dword v[6:7], v75, off offset:-256
	global_store_dwordx2 v[8:9], v[64:65], off
	global_store_dword v[6:7], v76, off
	global_store_dwordx2 v[8:9], v[66:67], off offset:512
	global_store_dword v[6:7], v77, off offset:256
	global_store_dwordx2 v[8:9], v[68:69], off offset:1024
	global_store_dword v[6:7], v78, off offset:512
	global_store_dwordx2 v[8:9], v[70:71], off offset:1536
	global_store_dword v[6:7], v79, off offset:768
	v_add_f32_dpp v13, v13, v13 row_ror:8 row_mask:0xf bank_mask:0xf bound_ctrl:1
	s_nop 1
	v_add_f32_dpp v13, v13, v13 row_ror:4 row_mask:0xf bank_mask:0xf bound_ctrl:1
	s_nop 1
	v_add_f32_dpp v13, v13, v13 row_ror:2 row_mask:0xf bank_mask:0xf bound_ctrl:1
	s_nop 1
	v_add_f32_dpp v3, v13, v13 row_ror:1 row_mask:0xf bank_mask:0xf bound_ctrl:1
	v_mov_b32_e32 v13, v3
	s_nop 1
	v_permlane16_swap_b32_e32 v3, v13
	v_add_f32_e32 v3, v3, v13
	v_mov_b32_e32 v13, v3
	s_nop 1
	v_permlane32_swap_b32_e32 v3, v13
	s_and_saveexec_b64 s[4:5], vcc
	v_add_f32_e32 v3, v3, v13
	global_store_dword v[4:5], v3, off
	s_or_b64 exec, exec, s[4:5]
	v_lshl_add_u64 v[4:5], v[4:5], 0, s[10:11]
	v_lshl_add_u64 v[6:7], v[6:7], 0, s[12:13]
	v_lshl_add_u64 v[8:9], v[8:9], 0, s[14:15]
	s_waitcnt vmcnt(41)
	v_cvt_pk_bf16_f32 v56, v84, v85
	v_cvt_pk_bf16_f32 v57, v86, v87
	v_cvt_pk_fp8_f32 v72, v84, v85
	v_mul_f32_e32 v13, v85, v85
	v_fmac_f32_e32 v13, v84, v84
	v_fmac_f32_e32 v13, v86, v86
	v_cvt_pk_fp8_f32 v72, v86, v87 op_sel:[0,0,1]
	v_fmac_f32_e32 v13, v87, v87
	s_waitcnt vmcnt(40)
	v_cvt_pk_bf16_f32 v58, v88, v89
	v_cvt_pk_bf16_f32 v59, v90, v91
	v_cvt_pk_fp8_f32 v73, v88, v89
	v_mul_f32_e32 v80, v89, v89
	v_fmac_f32_e32 v80, v88, v88
	v_fmac_f32_e32 v80, v90, v90
	v_cvt_pk_fp8_f32 v73, v90, v91 op_sel:[0,0,1]
	v_fmac_f32_e32 v80, v91, v91
	v_add_f32_e32 v13, v13, v80
	s_waitcnt vmcnt(39)
	v_cvt_pk_bf16_f32 v60, v92, v93
	v_cvt_pk_bf16_f32 v61, v94, v95
	v_cvt_pk_fp8_f32 v74, v92, v93
	v_mul_f32_e32 v80, v93, v93
	v_fmac_f32_e32 v80, v92, v92
	v_fmac_f32_e32 v80, v94, v94
	v_cvt_pk_fp8_f32 v74, v94, v95 op_sel:[0,0,1]
	v_fmac_f32_e32 v80, v95, v95
	v_add_f32_e32 v13, v13, v80
	s_waitcnt vmcnt(38)
	v_cvt_pk_bf16_f32 v62, v96, v97
	v_cvt_pk_bf16_f32 v63, v98, v99
	v_cvt_pk_fp8_f32 v75, v96, v97
	v_mul_f32_e32 v80, v97, v97
	v_fmac_f32_e32 v80, v96, v96
	v_fmac_f32_e32 v80, v98, v98
	v_cvt_pk_fp8_f32 v75, v98, v99 op_sel:[0,0,1]
	v_fmac_f32_e32 v80, v99, v99
	v_add_f32_e32 v13, v13, v80
	s_waitcnt vmcnt(37)
	v_cvt_pk_bf16_f32 v64, v100, v101
	v_cvt_pk_bf16_f32 v65, v102, v103
	v_cvt_pk_fp8_f32 v76, v100, v101
	v_mul_f32_e32 v80, v101, v101
	v_fmac_f32_e32 v80, v100, v100
	v_fmac_f32_e32 v80, v102, v102
	v_cvt_pk_fp8_f32 v76, v102, v103 op_sel:[0,0,1]
	v_fmac_f32_e32 v80, v103, v103
	v_add_f32_e32 v13, v13, v80
	s_waitcnt vmcnt(36)
	v_cvt_pk_bf16_f32 v66, v104, v105
	v_cvt_pk_bf16_f32 v67, v106, v107
	v_cvt_pk_fp8_f32 v77, v104, v105
	v_mul_f32_e32 v80, v105, v105
	v_fmac_f32_e32 v80, v104, v104
	v_fmac_f32_e32 v80, v106, v106
	v_cvt_pk_fp8_f32 v77, v106, v107 op_sel:[0,0,1]
	v_fmac_f32_e32 v80, v107, v107
	v_add_f32_e32 v13, v13, v80
	s_waitcnt vmcnt(35)
	v_cvt_pk_bf16_f32 v68, v108, v109
	v_cvt_pk_bf16_f32 v69, v110, v111
	v_cvt_pk_fp8_f32 v78, v108, v109
	v_mul_f32_e32 v80, v109, v109
	v_fmac_f32_e32 v80, v108, v108
	v_fmac_f32_e32 v80, v110, v110
	v_cvt_pk_fp8_f32 v78, v110, v111 op_sel:[0,0,1]
	v_fmac_f32_e32 v80, v111, v111
	v_add_f32_e32 v13, v13, v80
	s_waitcnt vmcnt(34)
	v_cvt_pk_bf16_f32 v70, v112, v113
	v_cvt_pk_bf16_f32 v71, v114, v115
	v_cvt_pk_fp8_f32 v79, v112, v113
	v_mul_f32_e32 v80, v113, v113
	v_fmac_f32_e32 v80, v112, v112
	v_fmac_f32_e32 v80, v114, v114
	v_cvt_pk_fp8_f32 v79, v114, v115 op_sel:[0,0,1]
	v_fmac_f32_e32 v80, v115, v115
	v_add_f32_e32 v13, v13, v80
	global_store_dwordx2 v[8:9], v[56:57], off offset:-2048
	global_store_dword v[6:7], v72, off offset:-1024
	global_store_dwordx2 v[8:9], v[58:59], off offset:-1536
	global_store_dword v[6:7], v73, off offset:-768
	global_store_dwordx2 v[8:9], v[60:61], off offset:-1024
	global_store_dword v[6:7], v74, off offset:-512
	global_store_dwordx2 v[8:9], v[62:63], off offset:-512
	global_store_dword v[6:7], v75, off offset:-256
	global_store_dwordx2 v[8:9], v[64:65], off
	global_store_dword v[6:7], v76, off
	global_store_dwordx2 v[8:9], v[66:67], off offset:512
	global_store_dword v[6:7], v77, off offset:256
	global_store_dwordx2 v[8:9], v[68:69], off offset:1024
	global_store_dword v[6:7], v78, off offset:512
	global_store_dwordx2 v[8:9], v[70:71], off offset:1536
	global_store_dword v[6:7], v79, off offset:768
	v_add_f32_dpp v13, v13, v13 row_ror:8 row_mask:0xf bank_mask:0xf bound_ctrl:1
	s_nop 1
	v_add_f32_dpp v13, v13, v13 row_ror:4 row_mask:0xf bank_mask:0xf bound_ctrl:1
	s_nop 1
	v_add_f32_dpp v13, v13, v13 row_ror:2 row_mask:0xf bank_mask:0xf bound_ctrl:1
	s_nop 1
	v_add_f32_dpp v3, v13, v13 row_ror:1 row_mask:0xf bank_mask:0xf bound_ctrl:1
	v_mov_b32_e32 v13, v3
	s_nop 1
	v_permlane16_swap_b32_e32 v3, v13
	v_add_f32_e32 v3, v3, v13
	v_mov_b32_e32 v13, v3
	s_nop 1
	v_permlane32_swap_b32_e32 v3, v13
	s_and_saveexec_b64 s[4:5], vcc
	v_add_f32_e32 v3, v3, v13
	global_store_dword v[4:5], v3, off
	s_or_b64 exec, exec, s[4:5]
	s_branch .LBB0_7
.Lx_generic:
	s_branch .LBB0_5
.LBB0_4:
	s_or_b64 exec, exec, s[4:5]
	v_add_u32_e32 v12, s8, v12
	v_cmp_lt_i32_e64 s[4:5], s2, v12
	v_lshl_add_u64 v[4:5], v[4:5], 0, s[10:11]
	v_lshl_add_u64 v[6:7], v[6:7], 0, s[12:13]
	v_lshl_add_u64 v[8:9], v[8:9], 0, s[14:15]
	s_or_b64 s[18:19], s[4:5], s[18:19]
	v_lshl_add_u64 v[10:11], v[10:11], 0, s[16:17]
	s_andn2_b64 exec, exec, s[18:19]
	s_cbranch_execz .LBB0_7
